# DMA-first load segments: LDS-DMA loads issued before the ds_read fragment loads in every K-loop segment (SALU-only address path)
# baseline (speedup 1.0000x reference)
; #define PG8_STAGE(bufoff, gbase, voff) do { _Pragma("unroll") for (int _i = 0; _i < 2; ++_i) \
;         __builtin_amdgcn_global_load_lds((const unsigned*)((const char*)(gbase) + (voff)[_i]), (PG8_LAS unsigned*)(lds + (bufoff) + ldsw + _i * 8192), 16, 0, 0); } while (0)
; #define PG8_LDA(dst, b, h) do { _Pragma("unroll") for (int m = 0; m < 4; ++m) _Pragma("unroll") for (int k = 0; k < 2; ++k) dst[m][k] = *(const PG8_LAS bf16x8*)(lds + PG8_SA(b, h) + aoff + m * 2048 + k * 1024); } while (0)
; #define PG8_LDB(dst, b, h) do { _Pragma("unroll") for (int n = 0; n < 2; ++n) _Pragma("unroll") for (int k = 0; k < 2; ++k) dst[n][k] = *(const PG8_LAS bf16x8*)(lds + PG8_SB(b, h) + boff + n * 2048 + k * 1024); } while (0)
; #define PG8_MMA(ai, bj, At, Bt) do { __builtin_amdgcn_s_setprio(1); _Pragma("unroll") for (int m = 0; m < 4; ++m) _Pragma("unroll") for (int n = 0; n < 2; ++n) _Pragma("unroll") for (int k = 0; k < 2; ++k) \
;         acc[ai][bj][m][n] = __builtin_amdgcn_mfma_f32_16x16x32_bf16(Bt[n][k], At[m][k], acc[ai][bj][m][n], 0, 0, 0); __builtin_amdgcn_s_setprio(0); } while (0)
; #define PG8_WAIT_V(n) asm volatile("s_waitcnt vmcnt(" #n ")" ::: "memory")
; #define PG8_WAIT_L(n) asm volatile("s_waitcnt lgkmcnt(" #n ")" ::: "memory")
; #define PG8_BAR __builtin_amdgcn_s_barrier()
; #define PG8_SCHED __builtin_amdgcn_sched_barrier(0)
; template <class Epi, class Sched, bool ALIGN_EPI = false, bool SP2 = false>
; __device__ __forceinline__ void gemm_phase(PG8_LAS unsigned char* lds, const Gemm g, const Sched& S, const Epi& E, int wave_s) {
;     ...
;             PG8_LDB(B0, 0, 0); PG8_LDB(B1, 0, 1); PG8_SCHED; PG8_LDA(At, 0, 0); PG8_STAGE(PG8_SA(1, 1), a1 + hstep, voffA);
;             PG8_WAIT_V(8); PG8_WAIT_L(0); PG8_BAR; PG8_MMA(0, 0, At, B0); PG8_MMA(0, 1, At, B1); PG8_BAR; PG8_SCHED;
;             PG8_LDA(At, 0, 1); PG8_STAGE(PG8_SB(0, 0), b2, voffB); PG8_STAGE(PG8_SB(0, 1), b2 + hstep, voffB); PG8_STAGE(PG8_SA(0, 0), a2, voffA);
;             PG8_WAIT_V(8); PG8_WAIT_L(0); PG8_BAR; PG8_MMA(1, 0, At, B0); PG8_MMA(1, 1, At, B1); PG8_BAR; PG8_SCHED;
.LBB0_41:
	s_add_u32 s48, s46, 0xfff00080
	s_addc_u32 s49, s47, -1
	s_cmp_eq_u32 s86, 60
	s_cselect_b32 s51, s31, s49
	s_cselect_b32 s50, s72, s48
	s_cselect_b32 s49, s35, s85
	s_cselect_b32 s48, s73, s84
	s_mov_b32 m0, s74
	s_nop 0
	global_load_lds_dwordx4 v138, s[46:47]
	s_mov_b32 m0, s75
	s_nop 0
	global_load_lds_dwordx4 v140, s[46:47]
	ds_read_b128 v[144:147], v158 offset:3072
	ds_read_b128 v[148:151], v158 offset:2048
	ds_read_b128 v[152:155], v158 offset:1024
	ds_read_b128 v[160:163], v158
	ds_read_b128 v[164:167], v157 offset:3072
	ds_read_b128 v[168:171], v157 offset:2048
	ds_read_b128 v[172:175], v157 offset:1024
	ds_read_b128 v[176:179], v157
	ds_read_b128 v[180:183], v159
	ds_read_b128 v[184:187], v159 offset:1024
	ds_read_b128 v[188:191], v159 offset:2048
	ds_read_b128 v[192:195], v159 offset:3072
	ds_read_b128 v[196:199], v159 offset:4096
	ds_read_b128 v[200:203], v159 offset:5120
	ds_read_b128 v[204:207], v159 offset:6144
	ds_read_b128 v[208:211], v159 offset:7168
	s_waitcnt vmcnt(8)
	s_waitcnt lgkmcnt(0)
	s_barrier
	v_mfma_f32_16x16x32_bf16 v[124:127], v[176:179], v[180:183], v[124:127]
	v_mfma_f32_16x16x32_bf16 v[124:127], v[172:175], v[184:187], v[124:127]
	v_mfma_f32_16x16x32_bf16 v[120:123], v[164:167], v[184:187], v[120:123]
	v_mfma_f32_16x16x32_bf16 v[120:123], v[168:171], v[180:183], v[120:123]
	v_mfma_f32_16x16x32_bf16 v[104:107], v[168:171], v[188:191], v[104:107]
	v_mfma_f32_16x16x32_bf16 v[104:107], v[164:167], v[192:195], v[104:107]
	v_mfma_f32_16x16x32_bf16 v[108:111], v[172:175], v[192:195], v[108:111]
	v_mfma_f32_16x16x32_bf16 v[108:111], v[176:179], v[188:191], v[108:111]
	v_mfma_f32_16x16x32_bf16 v[92:95], v[176:179], v[196:199], v[92:95]
	v_mfma_f32_16x16x32_bf16 v[92:95], v[172:175], v[200:203], v[92:95]
	v_mfma_f32_16x16x32_bf16 v[88:91], v[164:167], v[200:203], v[88:91]
	v_mfma_f32_16x16x32_bf16 v[88:91], v[168:171], v[196:199], v[88:91]
	v_mfma_f32_16x16x32_bf16 v[56:59], v[168:171], v[204:207], v[56:59]
	v_mfma_f32_16x16x32_bf16 v[56:59], v[164:167], v[208:211], v[56:59]
	v_mfma_f32_16x16x32_bf16 v[64:67], v[172:175], v[208:211], v[64:67]
	v_mfma_f32_16x16x32_bf16 v[64:67], v[176:179], v[204:207], v[64:67]
	v_mfma_f32_16x16x32_bf16 v[116:119], v[160:163], v[180:183], v[116:119]
	v_mfma_f32_16x16x32_bf16 v[116:119], v[152:155], v[184:187], v[116:119]
	v_mfma_f32_16x16x32_bf16 v[112:115], v[144:147], v[184:187], v[112:115]
	v_mfma_f32_16x16x32_bf16 v[112:115], v[148:151], v[180:183], v[112:115]
	v_mfma_f32_16x16x32_bf16 v[96:99], v[148:151], v[188:191], v[96:99]
	v_mfma_f32_16x16x32_bf16 v[96:99], v[144:147], v[192:195], v[96:99]
	v_mfma_f32_16x16x32_bf16 v[100:103], v[152:155], v[192:195], v[100:103]
	v_mfma_f32_16x16x32_bf16 v[100:103], v[160:163], v[188:191], v[100:103]
	v_mfma_f32_16x16x32_bf16 v[84:87], v[160:163], v[196:199], v[84:87]
	v_mfma_f32_16x16x32_bf16 v[84:87], v[152:155], v[200:203], v[84:87]
	v_mfma_f32_16x16x32_bf16 v[80:83], v[144:147], v[200:203], v[80:83]
	v_mfma_f32_16x16x32_bf16 v[80:83], v[148:151], v[196:199], v[80:83]
	v_mfma_f32_16x16x32_bf16 v[48:51], v[148:151], v[204:207], v[48:51]
	v_mfma_f32_16x16x32_bf16 v[48:51], v[144:147], v[208:211], v[48:51]
	v_mfma_f32_16x16x32_bf16 v[52:55], v[152:155], v[208:211], v[52:55]
	v_mfma_f32_16x16x32_bf16 v[52:55], v[160:163], v[204:207], v[52:55]
	s_barrier
	s_mov_b32 m0, s76
	s_nop 0
	s_add_u32 s88, s48, 0x100000
	global_load_lds_dwordx4 v132, s[48:49]
	s_mov_b32 m0, s77
	s_addc_u32 s89, s49, 0
	global_load_lds_dwordx4 v128, s[48:49]
	s_mov_b32 m0, s78
	s_nop 0
	global_load_lds_dwordx4 v132, s[88:89]
	s_mov_b32 m0, s79
	s_nop 0
	global_load_lds_dwordx4 v128, s[88:89]
	s_mov_b32 m0, s43
	s_nop 0
	global_load_lds_dwordx4 v134, s[50:51]
	s_mov_b32 m0, s57
	s_nop 0
	global_load_lds_dwordx4 v130, s[50:51]
	ds_read_b128 v[180:183], v159 offset:16384
	ds_read_b128 v[184:187], v159 offset:17408
	ds_read_b128 v[188:191], v159 offset:18432
	ds_read_b128 v[192:195], v159 offset:19456
	ds_read_b128 v[196:199], v159 offset:20480
	ds_read_b128 v[200:203], v159 offset:21504
	ds_read_b128 v[204:207], v159 offset:22528
	ds_read_b128 v[208:211], v159 offset:23552
	s_waitcnt vmcnt(8)
	s_waitcnt lgkmcnt(0)
	s_barrier
	v_mfma_f32_16x16x32_bf16 v[76:79], v[176:179], v[180:183], v[76:79]
	v_mfma_f32_16x16x32_bf16 v[76:79], v[172:175], v[184:187], v[76:79]
	v_mfma_f32_16x16x32_bf16 v[72:75], v[164:167], v[184:187], v[72:75]
	v_mfma_f32_16x16x32_bf16 v[72:75], v[168:171], v[180:183], v[72:75]
	v_mfma_f32_16x16x32_bf16 v[40:43], v[168:171], v[188:191], v[40:43]
	v_mfma_f32_16x16x32_bf16 v[40:43], v[164:167], v[192:195], v[40:43]
	v_mfma_f32_16x16x32_bf16 v[44:47], v[172:175], v[192:195], v[44:47]
	v_mfma_f32_16x16x32_bf16 v[44:47], v[176:179], v[188:191], v[44:47]
	v_mfma_f32_16x16x32_bf16 v[28:31], v[176:179], v[196:199], v[28:31]
	v_mfma_f32_16x16x32_bf16 v[28:31], v[172:175], v[200:203], v[28:31]
	v_mfma_f32_16x16x32_bf16 v[24:27], v[164:167], v[200:203], v[24:27]
	v_mfma_f32_16x16x32_bf16 v[24:27], v[168:171], v[196:199], v[24:27]
	v_mfma_f32_16x16x32_bf16 v[8:11], v[168:171], v[204:207], v[8:11]
	v_mfma_f32_16x16x32_bf16 v[8:11], v[164:167], v[208:211], v[8:11]
	v_mfma_f32_16x16x32_bf16 v[12:15], v[172:175], v[208:211], v[12:15]
	v_mfma_f32_16x16x32_bf16 v[12:15], v[176:179], v[204:207], v[12:15]
	v_mfma_f32_16x16x32_bf16 v[68:71], v[160:163], v[180:183], v[68:71]
	v_mfma_f32_16x16x32_bf16 v[68:71], v[152:155], v[184:187], v[68:71]
	v_mfma_f32_16x16x32_bf16 v[60:63], v[144:147], v[184:187], v[60:63]
	v_mfma_f32_16x16x32_bf16 v[60:63], v[148:151], v[180:183], v[60:63]
	v_mfma_f32_16x16x32_bf16 v[32:35], v[148:151], v[188:191], v[32:35]
	v_mfma_f32_16x16x32_bf16 v[32:35], v[144:147], v[192:195], v[32:35]
	v_mfma_f32_16x16x32_bf16 v[36:39], v[152:155], v[192:195], v[36:39]
	v_mfma_f32_16x16x32_bf16 v[36:39], v[160:163], v[188:191], v[36:39]
	v_mfma_f32_16x16x32_bf16 v[20:23], v[160:163], v[196:199], v[20:23]
	v_mfma_f32_16x16x32_bf16 v[20:23], v[152:155], v[200:203], v[20:23]
	v_mfma_f32_16x16x32_bf16 v[16:19], v[144:147], v[200:203], v[16:19]
	v_mfma_f32_16x16x32_bf16 v[16:19], v[148:151], v[196:199], v[16:19]
	v_mfma_f32_16x16x32_bf16 v[0:3], v[148:151], v[204:207], v[0:3]
	v_mfma_f32_16x16x32_bf16 v[0:3], v[144:147], v[208:211], v[0:3]
	v_mfma_f32_16x16x32_bf16 v[4:7], v[152:155], v[208:211], v[4:7]
	v_mfma_f32_16x16x32_bf16 v[4:7], v[160:163], v[204:207], v[4:7]
	s_barrier
; #define PG8_STAGE(bufoff, gbase, voff) do { _Pragma("unroll") for (int _i = 0; _i < 2; ++_i) \
;         __builtin_amdgcn_global_load_lds((const unsigned*)((const char*)(gbase) + (voff)[_i]), (PG8_LAS unsigned*)(lds + (bufoff) + ldsw + _i * 8192), 16, 0, 0); } while (0)
; #define PG8_LDA(dst, b, h) do { _Pragma("unroll") for (int m = 0; m < 4; ++m) _Pragma("unroll") for (int k = 0; k < 2; ++k) dst[m][k] = *(const PG8_LAS bf16x8*)(lds + PG8_SA(b, h) + aoff + m * 2048 + k * 1024); } while (0)
; #define PG8_LDB(dst, b, h) do { _Pragma("unroll") for (int n = 0; n < 2; ++n) _Pragma("unroll") for (int k = 0; k < 2; ++k) dst[n][k] = *(const PG8_LAS bf16x8*)(lds + PG8_SB(b, h) + boff + n * 2048 + k * 1024); } while (0)
; #define PG8_MMA(ai, bj, At, Bt) do { __builtin_amdgcn_s_setprio(1); _Pragma("unroll") for (int m = 0; m < 4; ++m) _Pragma("unroll") for (int n = 0; n < 2; ++n) _Pragma("unroll") for (int k = 0; k < 2; ++k) \
;         acc[ai][bj][m][n] = __builtin_amdgcn_mfma_f32_16x16x32_bf16(Bt[n][k], At[m][k], acc[ai][bj][m][n], 0, 0, 0); __builtin_amdgcn_s_setprio(0); } while (0)
; #define PG8_WAIT_V(n) asm volatile("s_waitcnt vmcnt(" #n ")" ::: "memory")
; #define PG8_WAIT_L(n) asm volatile("s_waitcnt lgkmcnt(" #n ")" ::: "memory")
; #define PG8_BAR __builtin_amdgcn_s_barrier()
; #define PG8_SCHED __builtin_amdgcn_sched_barrier(0)
; template <class Epi, class Sched, bool ALIGN_EPI = false, bool SP2 = false>
; __device__ __forceinline__ void gemm_phase(PG8_LAS unsigned char* lds, const Gemm g, const Sched& S, const Epi& E, int wave_s) {
;     ...
;             PG8_LDB(B0, 1, 0); PG8_LDB(B1, 1, 1); PG8_SCHED; PG8_LDA(At, 1, 0); PG8_STAGE(PG8_SA(0, 1), a2 + hstep, voffA);
;             PG8_WAIT_V(8); PG8_WAIT_L(0); PG8_BAR; PG8_MMA(0, 0, At, B0); PG8_MMA(0, 1, At, B1); PG8_BAR; PG8_SCHED;
;             PG8_LDA(At, 1, 1); PG8_STAGE(PG8_SB(1, 0), b3, voffB); PG8_STAGE(PG8_SB(1, 1), b3 + hstep, voffB); PG8_STAGE(PG8_SA(1, 0), a3, voffA);
;             PG8_WAIT_V(8); PG8_WAIT_L(0); PG8_BAR; PG8_MMA(1, 0, At, B0); PG8_MMA(1, 1, At, B1); PG8_BAR; PG8_SCHED;
	s_add_u32 s50, s50, 0x100000
	s_addc_u32 s51, s51, 0
	s_mov_b32 m0, s58
	s_nop 0
	global_load_lds_dwordx4 v134, s[50:51]
	s_mov_b32 m0, s59
	s_nop 0
	global_load_lds_dwordx4 v130, s[50:51]
	ds_read_b128 v[144:147], v142
	ds_read_b128 v[148:151], v142 offset:1024
	ds_read_b128 v[152:155], v142 offset:2048
	ds_read_b128 v[160:163], v142 offset:3072
	ds_read_b128 v[164:167], v143
	ds_read_b128 v[168:171], v143 offset:1024
	ds_read_b128 v[172:175], v143 offset:2048
	ds_read_b128 v[176:179], v143 offset:3072
	ds_read_b128 v[180:183], v159 offset:32768
	ds_read_b128 v[184:187], v159 offset:33792
	ds_read_b128 v[188:191], v159 offset:34816
	ds_read_b128 v[192:195], v159 offset:35840
	ds_read_b128 v[196:199], v159 offset:36864
	ds_read_b128 v[200:203], v159 offset:37888
	ds_read_b128 v[204:207], v159 offset:38912
	ds_read_b128 v[208:211], v159 offset:39936
	s_waitcnt vmcnt(8)
	s_waitcnt lgkmcnt(0)
	s_barrier
	v_mfma_f32_16x16x32_bf16 v[124:127], v[144:147], v[180:183], v[124:127]
	v_mfma_f32_16x16x32_bf16 v[124:127], v[148:151], v[184:187], v[124:127]
	v_mfma_f32_16x16x32_bf16 v[120:123], v[160:163], v[184:187], v[120:123]
	v_mfma_f32_16x16x32_bf16 v[120:123], v[152:155], v[180:183], v[120:123]
	v_mfma_f32_16x16x32_bf16 v[104:107], v[152:155], v[188:191], v[104:107]
	v_mfma_f32_16x16x32_bf16 v[104:107], v[160:163], v[192:195], v[104:107]
	v_mfma_f32_16x16x32_bf16 v[108:111], v[148:151], v[192:195], v[108:111]
	v_mfma_f32_16x16x32_bf16 v[108:111], v[144:147], v[188:191], v[108:111]
	v_mfma_f32_16x16x32_bf16 v[92:95], v[144:147], v[196:199], v[92:95]
	v_mfma_f32_16x16x32_bf16 v[92:95], v[148:151], v[200:203], v[92:95]
	v_mfma_f32_16x16x32_bf16 v[88:91], v[160:163], v[200:203], v[88:91]
	v_mfma_f32_16x16x32_bf16 v[88:91], v[152:155], v[196:199], v[88:91]
	v_mfma_f32_16x16x32_bf16 v[56:59], v[152:155], v[204:207], v[56:59]
	v_mfma_f32_16x16x32_bf16 v[56:59], v[160:163], v[208:211], v[56:59]
	v_mfma_f32_16x16x32_bf16 v[64:67], v[148:151], v[208:211], v[64:67]
	v_mfma_f32_16x16x32_bf16 v[64:67], v[144:147], v[204:207], v[64:67]
	v_mfma_f32_16x16x32_bf16 v[116:119], v[164:167], v[180:183], v[116:119]
	v_mfma_f32_16x16x32_bf16 v[116:119], v[168:171], v[184:187], v[116:119]
	v_mfma_f32_16x16x32_bf16 v[112:115], v[176:179], v[184:187], v[112:115]
	v_mfma_f32_16x16x32_bf16 v[112:115], v[172:175], v[180:183], v[112:115]
	v_mfma_f32_16x16x32_bf16 v[96:99], v[172:175], v[188:191], v[96:99]
	v_mfma_f32_16x16x32_bf16 v[96:99], v[176:179], v[192:195], v[96:99]
	v_mfma_f32_16x16x32_bf16 v[100:103], v[168:171], v[192:195], v[100:103]
	v_mfma_f32_16x16x32_bf16 v[100:103], v[164:167], v[188:191], v[100:103]
	v_mfma_f32_16x16x32_bf16 v[84:87], v[164:167], v[196:199], v[84:87]
	v_mfma_f32_16x16x32_bf16 v[84:87], v[168:171], v[200:203], v[84:87]
	v_mfma_f32_16x16x32_bf16 v[80:83], v[176:179], v[200:203], v[80:83]
	v_mfma_f32_16x16x32_bf16 v[80:83], v[172:175], v[196:199], v[80:83]
	v_mfma_f32_16x16x32_bf16 v[48:51], v[172:175], v[204:207], v[48:51]
	v_mfma_f32_16x16x32_bf16 v[48:51], v[176:179], v[208:211], v[48:51]
	v_mfma_f32_16x16x32_bf16 v[52:55], v[168:171], v[208:211], v[52:55]
	v_mfma_f32_16x16x32_bf16 v[52:55], v[164:167], v[204:207], v[52:55]
	s_barrier
	s_mov_b32 m0, s80
	s_nop 0
	s_add_u32 s94, s48, 0x80
	s_addc_u32 s95, s49, 0
	s_add_u32 s48, s48, 0x100080
	global_load_lds_dwordx4 v132, s[94:95]
	s_mov_b32 m0, s81
	s_addc_u32 s49, s49, 0
	global_load_lds_dwordx4 v128, s[94:95]
	s_mov_b32 m0, s82
	s_nop 0
	global_load_lds_dwordx4 v132, s[48:49]
	s_mov_b32 m0, s83
	s_nop 0
	global_load_lds_dwordx4 v128, s[48:49]
	s_mov_b32 m0, s64
	s_nop 0
	s_add_u32 s96, s50, 0xfff00080
	s_addc_u32 s97, s51, -1
	global_load_lds_dwordx4 v134, s[96:97]
	s_mov_b32 m0, s65
	s_nop 0
	global_load_lds_dwordx4 v130, s[96:97]
	ds_read_b128 v[180:183], v159 offset:49152
	ds_read_b128 v[184:187], v159 offset:50176
	ds_read_b128 v[188:191], v159 offset:51200
	ds_read_b128 v[192:195], v159 offset:52224
	ds_read_b128 v[196:199], v159 offset:53248
	ds_read_b128 v[200:203], v159 offset:54272
	ds_read_b128 v[204:207], v159 offset:55296
	ds_read_b128 v[208:211], v159 offset:56320
	s_waitcnt vmcnt(8)
	s_waitcnt lgkmcnt(0)
	s_barrier
	v_mfma_f32_16x16x32_bf16 v[76:79], v[144:147], v[180:183], v[76:79]
	v_mfma_f32_16x16x32_bf16 v[76:79], v[148:151], v[184:187], v[76:79]
	v_mfma_f32_16x16x32_bf16 v[72:75], v[160:163], v[184:187], v[72:75]
	v_mfma_f32_16x16x32_bf16 v[72:75], v[152:155], v[180:183], v[72:75]
	v_mfma_f32_16x16x32_bf16 v[40:43], v[152:155], v[188:191], v[40:43]
	v_mfma_f32_16x16x32_bf16 v[40:43], v[160:163], v[192:195], v[40:43]
	v_mfma_f32_16x16x32_bf16 v[44:47], v[148:151], v[192:195], v[44:47]
	v_mfma_f32_16x16x32_bf16 v[44:47], v[144:147], v[188:191], v[44:47]
	v_mfma_f32_16x16x32_bf16 v[28:31], v[144:147], v[196:199], v[28:31]
	v_mfma_f32_16x16x32_bf16 v[28:31], v[148:151], v[200:203], v[28:31]
	v_mfma_f32_16x16x32_bf16 v[24:27], v[160:163], v[200:203], v[24:27]
	v_mfma_f32_16x16x32_bf16 v[24:27], v[152:155], v[196:199], v[24:27]
	v_mfma_f32_16x16x32_bf16 v[8:11], v[152:155], v[204:207], v[8:11]
	v_mfma_f32_16x16x32_bf16 v[8:11], v[160:163], v[208:211], v[8:11]
	v_mfma_f32_16x16x32_bf16 v[12:15], v[148:151], v[208:211], v[12:15]
	v_mfma_f32_16x16x32_bf16 v[12:15], v[144:147], v[204:207], v[12:15]
	v_mfma_f32_16x16x32_bf16 v[68:71], v[164:167], v[180:183], v[68:71]
	v_mfma_f32_16x16x32_bf16 v[68:71], v[168:171], v[184:187], v[68:71]
	v_mfma_f32_16x16x32_bf16 v[60:63], v[176:179], v[184:187], v[60:63]
	v_mfma_f32_16x16x32_bf16 v[60:63], v[172:175], v[180:183], v[60:63]
	v_mfma_f32_16x16x32_bf16 v[32:35], v[172:175], v[188:191], v[32:35]
	v_mfma_f32_16x16x32_bf16 v[32:35], v[176:179], v[192:195], v[32:35]
	v_mfma_f32_16x16x32_bf16 v[36:39], v[168:171], v[192:195], v[36:39]
	v_mfma_f32_16x16x32_bf16 v[36:39], v[164:167], v[188:191], v[36:39]
	v_mfma_f32_16x16x32_bf16 v[20:23], v[164:167], v[196:199], v[20:23]
	v_mfma_f32_16x16x32_bf16 v[20:23], v[168:171], v[200:203], v[20:23]
	v_mfma_f32_16x16x32_bf16 v[16:19], v[176:179], v[200:203], v[16:19]
	v_mfma_f32_16x16x32_bf16 v[16:19], v[172:175], v[196:199], v[16:19]
	v_mfma_f32_16x16x32_bf16 v[0:3], v[172:175], v[204:207], v[0:3]
	v_mfma_f32_16x16x32_bf16 v[0:3], v[176:179], v[208:211], v[0:3]
	v_mfma_f32_16x16x32_bf16 v[4:7], v[168:171], v[208:211], v[4:7]
	v_mfma_f32_16x16x32_bf16 v[4:7], v[164:167], v[204:207], v[4:7]
	s_barrier
	s_add_i32 s86, s86, 2
	s_add_u32 s46, s46, 0x100
	s_addc_u32 s47, s47, 0
	s_add_u32 s84, s84, 0x100
	s_addc_u32 s85, s85, 0
	s_cmp_gt_u32 s86, 61
	s_cbranch_scc0 .LBB0_41
	s_and_b64 vcc, exec, s[14:15]
	s_cbranch_vccz .LBB0_44
	s_barrier

; #define PG8_STAGE(bufoff, gbase, voff) do { _Pragma("unroll") for (int _i = 0; _i < 2; ++_i) \
;         __builtin_amdgcn_global_load_lds((const unsigned*)((const char*)(gbase) + (voff)[_i]), (PG8_LAS unsigned*)(lds + (bufoff) + ldsw + _i * 8192), 16, 0, 0); } while (0)
; #define PG8_LDA(dst, b, h) do { _Pragma("unroll") for (int m = 0; m < 4; ++m) _Pragma("unroll") for (int k = 0; k < 2; ++k) dst[m][k] = *(const PG8_LAS bf16x8*)(lds + PG8_SA(b, h) + aoff + m * 2048 + k * 1024); } while (0)
; #define PG8_LDB(dst, b, h) do { _Pragma("unroll") for (int n = 0; n < 2; ++n) _Pragma("unroll") for (int k = 0; k < 2; ++k) dst[n][k] = *(const PG8_LAS bf16x8*)(lds + PG8_SB(b, h) + boff + n * 2048 + k * 1024); } while (0)
; #define PG8_MMA(ai, bj, At, Bt) do { __builtin_amdgcn_s_setprio(1); _Pragma("unroll") for (int m = 0; m < 4; ++m) _Pragma("unroll") for (int n = 0; n < 2; ++n) _Pragma("unroll") for (int k = 0; k < 2; ++k) \
;         acc[ai][bj][m][n] = __builtin_amdgcn_mfma_f32_16x16x32_bf16(Bt[n][k], At[m][k], acc[ai][bj][m][n], 0, 0, 0); __builtin_amdgcn_s_setprio(0); } while (0)
; #define PG8_WAIT_V(n) asm volatile("s_waitcnt vmcnt(" #n ")" ::: "memory")
; #define PG8_WAIT_L(n) asm volatile("s_waitcnt lgkmcnt(" #n ")" ::: "memory")
; #define PG8_BAR __builtin_amdgcn_s_barrier()
; #define PG8_SCHED __builtin_amdgcn_sched_barrier(0)
; template <class Epi, class Sched, bool ALIGN_EPI = false, bool SP2 = false>
; __device__ __forceinline__ void gemm_phase(PG8_LAS unsigned char* lds, const Gemm g, const Sched& S, const Epi& E, int wave_s) {
;     ...
;             PG8_LDB(B0, 0, 0); PG8_LDB(B1, 0, 1); PG8_SCHED; PG8_LDA(At, 0, 0); PG8_STAGE(PG8_SA(1, 1), a1 + hstep, voffA);
;             PG8_WAIT_V(8); PG8_WAIT_L(0); PG8_BAR; PG8_MMA(0, 0, At, B0); PG8_MMA(0, 1, At, B1); PG8_BAR; PG8_SCHED;
;             PG8_LDA(At, 0, 1); PG8_STAGE(PG8_SB(0, 0), b2, voffB); PG8_STAGE(PG8_SB(0, 1), b2 + hstep, voffB); PG8_STAGE(PG8_SA(0, 0), a2, voffA);
;             PG8_WAIT_V(8); PG8_WAIT_L(0); PG8_BAR; PG8_MMA(1, 0, At, B0); PG8_MMA(1, 1, At, B1); PG8_BAR; PG8_SCHED;
.LBB0_1200:
	s_add_u32 s45, s50, 0xfff00080
	s_addc_u32 s52, s51, -1
	s_cmp_eq_u32 s85, s43
	s_cselect_b32 s55, s47, s52
	s_cselect_b32 s54, s46, s45
	s_cselect_b32 s53, s49, s41
	s_cselect_b32 s52, s48, s7
	s_add_i32 m0, s9, 0xc000
	s_nop 0
	global_load_lds_dwordx4 v192, s[50:51]
	s_add_i32 m0, s9, 0xe000
	s_nop 0
	global_load_lds_dwordx4 v194, s[50:51]
	ds_read_b128 v[128:131], v211
	ds_read_b128 v[132:135], v211 offset:1024
	ds_read_b128 v[136:139], v211 offset:2048
	ds_read_b128 v[140:143], v211 offset:3072
	ds_read_b128 v[144:147], v212
	ds_read_b128 v[148:151], v212 offset:1024
	ds_read_b128 v[152:155], v212 offset:2048
	ds_read_b128 v[156:159], v212 offset:3072
	ds_read_b128 v[160:163], v213
	ds_read_b128 v[164:167], v213 offset:1024
	ds_read_b128 v[168:171], v213 offset:2048
	ds_read_b128 v[172:175], v213 offset:3072
	ds_read_b128 v[176:179], v213 offset:4096
	ds_read_b128 v[180:183], v213 offset:5120
	ds_read_b128 v[196:199], v213 offset:6144
	ds_read_b128 v[200:203], v213 offset:7168
	s_waitcnt vmcnt(8)
	s_waitcnt lgkmcnt(0)
	s_barrier
	v_mfma_f32_16x16x32_bf16 v[124:127], v[128:131], v[160:163], v[124:127]
	v_mfma_f32_16x16x32_bf16 v[124:127], v[132:135], v[164:167], v[124:127]
	v_mfma_f32_16x16x32_bf16 v[120:123], v[140:143], v[164:167], v[120:123]
	v_mfma_f32_16x16x32_bf16 v[120:123], v[136:139], v[160:163], v[120:123]
	v_mfma_f32_16x16x32_bf16 v[104:107], v[136:139], v[168:171], v[104:107]
	v_mfma_f32_16x16x32_bf16 v[104:107], v[140:143], v[172:175], v[104:107]
	v_mfma_f32_16x16x32_bf16 v[108:111], v[132:135], v[172:175], v[108:111]
	v_mfma_f32_16x16x32_bf16 v[108:111], v[128:131], v[168:171], v[108:111]
	v_mfma_f32_16x16x32_bf16 v[92:95], v[128:131], v[176:179], v[92:95]
	v_mfma_f32_16x16x32_bf16 v[92:95], v[132:135], v[180:183], v[92:95]
	v_mfma_f32_16x16x32_bf16 v[88:91], v[140:143], v[180:183], v[88:91]
	v_mfma_f32_16x16x32_bf16 v[88:91], v[136:139], v[176:179], v[88:91]
	v_mfma_f32_16x16x32_bf16 v[72:75], v[136:139], v[196:199], v[72:75]
	v_mfma_f32_16x16x32_bf16 v[72:75], v[140:143], v[200:203], v[72:75]
	v_mfma_f32_16x16x32_bf16 v[76:79], v[132:135], v[200:203], v[76:79]
	v_mfma_f32_16x16x32_bf16 v[76:79], v[128:131], v[196:199], v[76:79]
	v_mfma_f32_16x16x32_bf16 v[116:119], v[144:147], v[160:163], v[116:119]
	v_mfma_f32_16x16x32_bf16 v[116:119], v[148:151], v[164:167], v[116:119]
	v_mfma_f32_16x16x32_bf16 v[112:115], v[156:159], v[164:167], v[112:115]
	v_mfma_f32_16x16x32_bf16 v[112:115], v[152:155], v[160:163], v[112:115]
	v_mfma_f32_16x16x32_bf16 v[96:99], v[152:155], v[168:171], v[96:99]
	v_mfma_f32_16x16x32_bf16 v[96:99], v[156:159], v[172:175], v[96:99]
	v_mfma_f32_16x16x32_bf16 v[100:103], v[148:151], v[172:175], v[100:103]
	v_mfma_f32_16x16x32_bf16 v[100:103], v[144:147], v[168:171], v[100:103]
	v_mfma_f32_16x16x32_bf16 v[84:87], v[144:147], v[176:179], v[84:87]
	v_mfma_f32_16x16x32_bf16 v[84:87], v[148:151], v[180:183], v[84:87]
	v_mfma_f32_16x16x32_bf16 v[80:83], v[156:159], v[180:183], v[80:83]
	v_mfma_f32_16x16x32_bf16 v[80:83], v[152:155], v[176:179], v[80:83]
	v_mfma_f32_16x16x32_bf16 v[64:67], v[152:155], v[196:199], v[64:67]
	v_mfma_f32_16x16x32_bf16 v[64:67], v[156:159], v[200:203], v[64:67]
	v_mfma_f32_16x16x32_bf16 v[68:71], v[148:151], v[200:203], v[68:71]
	v_mfma_f32_16x16x32_bf16 v[68:71], v[144:147], v[196:199], v[68:71]
	s_barrier
	s_add_i32 s45, s75, s60
	s_mov_b32 m0, s45
	s_nop 0
	global_load_lds_dwordx4 v186, s[52:53]
	s_add_i32 m0, s45, 0x2000
	s_add_u32 s86, s52, 0x100000
	s_addc_u32 s87, s53, 0
	s_add_i32 s45, s76, s60
	global_load_lds_dwordx4 v190, s[52:53]
	s_mov_b32 m0, s45
	s_nop 0
	global_load_lds_dwordx4 v186, s[86:87]
	s_add_i32 m0, s45, 0x2000
	s_nop 0
	global_load_lds_dwordx4 v190, s[86:87]
	s_mov_b32 m0, s9
	s_nop 0
	global_load_lds_dwordx4 v184, s[54:55]
	s_mov_b32 m0, s61
	s_nop 0
	global_load_lds_dwordx4 v188, s[54:55]
	ds_read_b128 v[160:163], v213 offset:16384
	ds_read_b128 v[164:167], v213 offset:17408
	ds_read_b128 v[168:171], v213 offset:18432
	ds_read_b128 v[172:175], v213 offset:19456
	ds_read_b128 v[176:179], v213 offset:20480
	ds_read_b128 v[180:183], v213 offset:21504
	ds_read_b128 v[196:199], v213 offset:22528
	ds_read_b128 v[200:203], v213 offset:23552
	s_waitcnt vmcnt(8)
	s_waitcnt lgkmcnt(0)
	s_barrier
	v_mfma_f32_16x16x32_bf16 v[60:63], v[128:131], v[160:163], v[60:63]
	v_mfma_f32_16x16x32_bf16 v[60:63], v[132:135], v[164:167], v[60:63]
	v_mfma_f32_16x16x32_bf16 v[56:59], v[140:143], v[164:167], v[56:59]
	v_mfma_f32_16x16x32_bf16 v[56:59], v[136:139], v[160:163], v[56:59]
	v_mfma_f32_16x16x32_bf16 v[40:43], v[136:139], v[168:171], v[40:43]
	v_mfma_f32_16x16x32_bf16 v[40:43], v[140:143], v[172:175], v[40:43]
	v_mfma_f32_16x16x32_bf16 v[44:47], v[132:135], v[172:175], v[44:47]
	v_mfma_f32_16x16x32_bf16 v[44:47], v[128:131], v[168:171], v[44:47]
	v_mfma_f32_16x16x32_bf16 v[28:31], v[128:131], v[176:179], v[28:31]
	v_mfma_f32_16x16x32_bf16 v[28:31], v[132:135], v[180:183], v[28:31]
	v_mfma_f32_16x16x32_bf16 v[24:27], v[140:143], v[180:183], v[24:27]
	v_mfma_f32_16x16x32_bf16 v[24:27], v[136:139], v[176:179], v[24:27]
	v_mfma_f32_16x16x32_bf16 v[8:11], v[136:139], v[196:199], v[8:11]
	v_mfma_f32_16x16x32_bf16 v[8:11], v[140:143], v[200:203], v[8:11]
	v_mfma_f32_16x16x32_bf16 v[12:15], v[132:135], v[200:203], v[12:15]
	v_mfma_f32_16x16x32_bf16 v[12:15], v[128:131], v[196:199], v[12:15]
	v_mfma_f32_16x16x32_bf16 v[52:55], v[144:147], v[160:163], v[52:55]
	v_mfma_f32_16x16x32_bf16 v[52:55], v[148:151], v[164:167], v[52:55]
	v_mfma_f32_16x16x32_bf16 v[48:51], v[156:159], v[164:167], v[48:51]
	v_mfma_f32_16x16x32_bf16 v[48:51], v[152:155], v[160:163], v[48:51]
	v_mfma_f32_16x16x32_bf16 v[32:35], v[152:155], v[168:171], v[32:35]
	v_mfma_f32_16x16x32_bf16 v[32:35], v[156:159], v[172:175], v[32:35]
	v_mfma_f32_16x16x32_bf16 v[36:39], v[148:151], v[172:175], v[36:39]
	v_mfma_f32_16x16x32_bf16 v[36:39], v[144:147], v[168:171], v[36:39]
	v_mfma_f32_16x16x32_bf16 v[20:23], v[144:147], v[176:179], v[20:23]
	v_mfma_f32_16x16x32_bf16 v[20:23], v[148:151], v[180:183], v[20:23]
	v_mfma_f32_16x16x32_bf16 v[16:19], v[156:159], v[180:183], v[16:19]
	v_mfma_f32_16x16x32_bf16 v[16:19], v[152:155], v[176:179], v[16:19]
	v_mfma_f32_16x16x32_bf16 v[0:3], v[152:155], v[196:199], v[0:3]
	v_mfma_f32_16x16x32_bf16 v[0:3], v[156:159], v[200:203], v[0:3]
	v_mfma_f32_16x16x32_bf16 v[4:7], v[148:151], v[200:203], v[4:7]
	v_mfma_f32_16x16x32_bf16 v[4:7], v[144:147], v[196:199], v[4:7]
	s_barrier
; #define PG8_STAGE(bufoff, gbase, voff) do { _Pragma("unroll") for (int _i = 0; _i < 2; ++_i) \
;         __builtin_amdgcn_global_load_lds((const unsigned*)((const char*)(gbase) + (voff)[_i]), (PG8_LAS unsigned*)(lds + (bufoff) + ldsw + _i * 8192), 16, 0, 0); } while (0)
; #define PG8_LDA(dst, b, h) do { _Pragma("unroll") for (int m = 0; m < 4; ++m) _Pragma("unroll") for (int k = 0; k < 2; ++k) dst[m][k] = *(const PG8_LAS bf16x8*)(lds + PG8_SA(b, h) + aoff + m * 2048 + k * 1024); } while (0)
; #define PG8_LDB(dst, b, h) do { _Pragma("unroll") for (int n = 0; n < 2; ++n) _Pragma("unroll") for (int k = 0; k < 2; ++k) dst[n][k] = *(const PG8_LAS bf16x8*)(lds + PG8_SB(b, h) + boff + n * 2048 + k * 1024); } while (0)
; #define PG8_MMA(ai, bj, At, Bt) do { __builtin_amdgcn_s_setprio(1); _Pragma("unroll") for (int m = 0; m < 4; ++m) _Pragma("unroll") for (int n = 0; n < 2; ++n) _Pragma("unroll") for (int k = 0; k < 2; ++k) \
;         acc[ai][bj][m][n] = __builtin_amdgcn_mfma_f32_16x16x32_bf16(Bt[n][k], At[m][k], acc[ai][bj][m][n], 0, 0, 0); __builtin_amdgcn_s_setprio(0); } while (0)
; #define PG8_WAIT_V(n) asm volatile("s_waitcnt vmcnt(" #n ")" ::: "memory")
; #define PG8_WAIT_L(n) asm volatile("s_waitcnt lgkmcnt(" #n ")" ::: "memory")
; #define PG8_BAR __builtin_amdgcn_s_barrier()
; #define PG8_SCHED __builtin_amdgcn_sched_barrier(0)
; template <class Epi, class Sched, bool ALIGN_EPI = false, bool SP2 = false>
; __device__ __forceinline__ void gemm_phase(PG8_LAS unsigned char* lds, const Gemm g, const Sched& S, const Epi& E, int wave_s) {
;     ...
;             PG8_LDB(B0, 1, 0); PG8_LDB(B1, 1, 1); PG8_SCHED; PG8_LDA(At, 1, 0); PG8_STAGE(PG8_SA(0, 1), a2 + hstep, voffA);
;             PG8_WAIT_V(8); PG8_WAIT_L(0); PG8_BAR; PG8_MMA(0, 0, At, B0); PG8_MMA(0, 1, At, B1); PG8_BAR; PG8_SCHED;
;             PG8_LDA(At, 1, 1); PG8_STAGE(PG8_SB(1, 0), b3, voffB); PG8_STAGE(PG8_SB(1, 1), b3 + hstep, voffB); PG8_STAGE(PG8_SA(1, 0), a3, voffA);
;             PG8_WAIT_V(8); PG8_WAIT_L(0); PG8_BAR; PG8_MMA(1, 0, At, B0); PG8_MMA(1, 1, At, B1); PG8_BAR; PG8_SCHED;
	s_add_i32 s45, 0, 0x18000
	s_add_i32 s86, 0, 0x1c000
	s_add_u32 s54, s54, 0x100000
	s_addc_u32 s55, s55, 0
	s_mov_b32 m0, s62
	s_nop 0
	global_load_lds_dwordx4 v184, s[54:55]
	s_mov_b32 m0, s63
	s_nop 0
	global_load_lds_dwordx4 v188, s[54:55]
	ds_read_b128 v[128:131], v230
	ds_read_b128 v[132:135], v230 offset:1024
	ds_read_b128 v[136:139], v230 offset:2048
	ds_read_b128 v[140:143], v230 offset:3072
	ds_read_b128 v[144:147], v231
	ds_read_b128 v[148:151], v231 offset:1024
	ds_read_b128 v[152:155], v231 offset:2048
	ds_read_b128 v[156:159], v231 offset:3072
	ds_read_b128 v[160:163], v213 offset:32768
	ds_read_b128 v[164:167], v213 offset:33792
	ds_read_b128 v[168:171], v213 offset:34816
	ds_read_b128 v[172:175], v213 offset:35840
	ds_read_b128 v[176:179], v213 offset:36864
	ds_read_b128 v[180:183], v213 offset:37888
	ds_read_b128 v[196:199], v213 offset:38912
	ds_read_b128 v[200:203], v213 offset:39936
	s_waitcnt vmcnt(8)
	s_waitcnt lgkmcnt(0)
	s_barrier
	v_mfma_f32_16x16x32_bf16 v[124:127], v[128:131], v[160:163], v[124:127]
	v_mfma_f32_16x16x32_bf16 v[124:127], v[132:135], v[164:167], v[124:127]
	v_mfma_f32_16x16x32_bf16 v[120:123], v[140:143], v[164:167], v[120:123]
	v_mfma_f32_16x16x32_bf16 v[120:123], v[136:139], v[160:163], v[120:123]
	v_mfma_f32_16x16x32_bf16 v[104:107], v[136:139], v[168:171], v[104:107]
	v_mfma_f32_16x16x32_bf16 v[104:107], v[140:143], v[172:175], v[104:107]
	v_mfma_f32_16x16x32_bf16 v[108:111], v[132:135], v[172:175], v[108:111]
	v_mfma_f32_16x16x32_bf16 v[108:111], v[128:131], v[168:171], v[108:111]
	v_mfma_f32_16x16x32_bf16 v[92:95], v[128:131], v[176:179], v[92:95]
	v_mfma_f32_16x16x32_bf16 v[92:95], v[132:135], v[180:183], v[92:95]
	v_mfma_f32_16x16x32_bf16 v[88:91], v[140:143], v[180:183], v[88:91]
	v_mfma_f32_16x16x32_bf16 v[88:91], v[136:139], v[176:179], v[88:91]
	v_mfma_f32_16x16x32_bf16 v[72:75], v[136:139], v[196:199], v[72:75]
	v_mfma_f32_16x16x32_bf16 v[72:75], v[140:143], v[200:203], v[72:75]
	v_mfma_f32_16x16x32_bf16 v[76:79], v[132:135], v[200:203], v[76:79]
	v_mfma_f32_16x16x32_bf16 v[76:79], v[128:131], v[196:199], v[76:79]
	v_mfma_f32_16x16x32_bf16 v[116:119], v[144:147], v[160:163], v[116:119]
	v_mfma_f32_16x16x32_bf16 v[116:119], v[148:151], v[164:167], v[116:119]
	v_mfma_f32_16x16x32_bf16 v[112:115], v[156:159], v[164:167], v[112:115]
	v_mfma_f32_16x16x32_bf16 v[112:115], v[152:155], v[160:163], v[112:115]
	v_mfma_f32_16x16x32_bf16 v[96:99], v[152:155], v[168:171], v[96:99]
	v_mfma_f32_16x16x32_bf16 v[96:99], v[156:159], v[172:175], v[96:99]
	v_mfma_f32_16x16x32_bf16 v[100:103], v[148:151], v[172:175], v[100:103]
	v_mfma_f32_16x16x32_bf16 v[100:103], v[144:147], v[168:171], v[100:103]
	v_mfma_f32_16x16x32_bf16 v[84:87], v[144:147], v[176:179], v[84:87]
	v_mfma_f32_16x16x32_bf16 v[84:87], v[148:151], v[180:183], v[84:87]
	v_mfma_f32_16x16x32_bf16 v[80:83], v[156:159], v[180:183], v[80:83]
	v_mfma_f32_16x16x32_bf16 v[80:83], v[152:155], v[176:179], v[80:83]
	v_mfma_f32_16x16x32_bf16 v[64:67], v[152:155], v[196:199], v[64:67]
	v_mfma_f32_16x16x32_bf16 v[64:67], v[156:159], v[200:203], v[64:67]
	v_mfma_f32_16x16x32_bf16 v[68:71], v[148:151], v[200:203], v[68:71]
	v_mfma_f32_16x16x32_bf16 v[68:71], v[144:147], v[196:199], v[68:71]
	s_barrier
	s_add_i32 s45, s45, s60
	s_mov_b32 m0, s45
	s_add_u32 s94, s52, 0x80
	s_addc_u32 s95, s53, 0
	global_load_lds_dwordx4 v186, s[94:95]
	s_add_i32 m0, s45, 0x2000
	s_add_u32 s52, s52, 0x100080
	s_addc_u32 s53, s53, 0
	s_add_i32 s45, s86, s60
	global_load_lds_dwordx4 v190, s[94:95]
	s_mov_b32 m0, s45
	s_nop 0
	global_load_lds_dwordx4 v186, s[52:53]
	s_add_i32 m0, s45, 0x2000
	s_nop 0
	global_load_lds_dwordx4 v190, s[52:53]
	s_mov_b32 m0, s70
	s_nop 0
	s_add_u32 s96, s54, 0xfff00080
	s_addc_u32 s97, s55, -1
	global_load_lds_dwordx4 v184, s[96:97]
	s_mov_b32 m0, s71
	s_nop 0
	global_load_lds_dwordx4 v188, s[96:97]
	ds_read_b128 v[160:163], v213 offset:49152
	ds_read_b128 v[164:167], v213 offset:50176
	ds_read_b128 v[168:171], v213 offset:51200
	ds_read_b128 v[172:175], v213 offset:52224
	ds_read_b128 v[176:179], v213 offset:53248
	ds_read_b128 v[180:183], v213 offset:54272
	ds_read_b128 v[196:199], v213 offset:55296
	ds_read_b128 v[200:203], v213 offset:56320
	s_waitcnt vmcnt(8)
	s_waitcnt lgkmcnt(0)
	s_barrier
	v_mfma_f32_16x16x32_bf16 v[60:63], v[128:131], v[160:163], v[60:63]
	v_mfma_f32_16x16x32_bf16 v[60:63], v[132:135], v[164:167], v[60:63]
	v_mfma_f32_16x16x32_bf16 v[56:59], v[140:143], v[164:167], v[56:59]
	v_mfma_f32_16x16x32_bf16 v[56:59], v[136:139], v[160:163], v[56:59]
	v_mfma_f32_16x16x32_bf16 v[40:43], v[136:139], v[168:171], v[40:43]
	v_mfma_f32_16x16x32_bf16 v[40:43], v[140:143], v[172:175], v[40:43]
	v_mfma_f32_16x16x32_bf16 v[44:47], v[132:135], v[172:175], v[44:47]
	v_mfma_f32_16x16x32_bf16 v[44:47], v[128:131], v[168:171], v[44:47]
	v_mfma_f32_16x16x32_bf16 v[28:31], v[128:131], v[176:179], v[28:31]
	v_mfma_f32_16x16x32_bf16 v[28:31], v[132:135], v[180:183], v[28:31]
	v_mfma_f32_16x16x32_bf16 v[24:27], v[140:143], v[180:183], v[24:27]
	v_mfma_f32_16x16x32_bf16 v[24:27], v[136:139], v[176:179], v[24:27]
	v_mfma_f32_16x16x32_bf16 v[8:11], v[136:139], v[196:199], v[8:11]
	v_mfma_f32_16x16x32_bf16 v[8:11], v[140:143], v[200:203], v[8:11]
	v_mfma_f32_16x16x32_bf16 v[12:15], v[132:135], v[200:203], v[12:15]
	v_mfma_f32_16x16x32_bf16 v[12:15], v[128:131], v[196:199], v[12:15]
	v_mfma_f32_16x16x32_bf16 v[52:55], v[144:147], v[160:163], v[52:55]
	v_mfma_f32_16x16x32_bf16 v[52:55], v[148:151], v[164:167], v[52:55]
	v_mfma_f32_16x16x32_bf16 v[48:51], v[156:159], v[164:167], v[48:51]
	v_mfma_f32_16x16x32_bf16 v[48:51], v[152:155], v[160:163], v[48:51]
	v_mfma_f32_16x16x32_bf16 v[32:35], v[152:155], v[168:171], v[32:35]
	v_mfma_f32_16x16x32_bf16 v[32:35], v[156:159], v[172:175], v[32:35]
	v_mfma_f32_16x16x32_bf16 v[36:39], v[148:151], v[172:175], v[36:39]
	v_mfma_f32_16x16x32_bf16 v[36:39], v[144:147], v[168:171], v[36:39]
	v_mfma_f32_16x16x32_bf16 v[20:23], v[144:147], v[176:179], v[20:23]
	v_mfma_f32_16x16x32_bf16 v[20:23], v[148:151], v[180:183], v[20:23]
	v_mfma_f32_16x16x32_bf16 v[16:19], v[156:159], v[180:183], v[16:19]
	v_mfma_f32_16x16x32_bf16 v[16:19], v[152:155], v[176:179], v[16:19]
	v_mfma_f32_16x16x32_bf16 v[0:3], v[152:155], v[196:199], v[0:3]
	v_mfma_f32_16x16x32_bf16 v[0:3], v[156:159], v[200:203], v[0:3]
	v_mfma_f32_16x16x32_bf16 v[4:7], v[148:151], v[200:203], v[4:7]
	v_mfma_f32_16x16x32_bf16 v[4:7], v[144:147], v[196:199], v[4:7]
	s_barrier
	s_add_i32 s45, s43, 2
	s_add_u32 s50, s50, 0x100
	s_addc_u32 s51, s51, 0
	s_add_u32 s7, s7, 0x100
	s_addc_u32 s41, s41, 0
	s_cmp_ge_i32 s43, s85
	s_mov_b32 s43, s45
	s_cbranch_scc0 .LBB0_1200
	s_and_b64 vcc, exec, s[20:21]
	s_cbranch_vccz .LBB0_1203
	s_barrier

; #define PG8_STAGE(bufoff, gbase, voff) do { _Pragma("unroll") for (int _i = 0; _i < 2; ++_i) \
;         __builtin_amdgcn_global_load_lds((const unsigned*)((const char*)(gbase) + (voff)[_i]), (PG8_LAS unsigned*)(lds + (bufoff) + ldsw + _i * 8192), 16, 0, 0); } while (0)
; #define PG8_LDA(dst, b, h) do { _Pragma("unroll") for (int m = 0; m < 4; ++m) _Pragma("unroll") for (int k = 0; k < 2; ++k) dst[m][k] = *(const PG8_LAS bf16x8*)(lds + PG8_SA(b, h) + aoff + m * 2048 + k * 1024); } while (0)
; #define PG8_LDB(dst, b, h) do { _Pragma("unroll") for (int n = 0; n < 2; ++n) _Pragma("unroll") for (int k = 0; k < 2; ++k) dst[n][k] = *(const PG8_LAS bf16x8*)(lds + PG8_SB(b, h) + boff + n * 2048 + k * 1024); } while (0)
; #define PG8_MMA(ai, bj, At, Bt) do { __builtin_amdgcn_s_setprio(1); _Pragma("unroll") for (int m = 0; m < 4; ++m) _Pragma("unroll") for (int n = 0; n < 2; ++n) _Pragma("unroll") for (int k = 0; k < 2; ++k) \
;         acc[ai][bj][m][n] = __builtin_amdgcn_mfma_f32_16x16x32_bf16(Bt[n][k], At[m][k], acc[ai][bj][m][n], 0, 0, 0); __builtin_amdgcn_s_setprio(0); } while (0)
; #define PG8_WAIT_V(n) asm volatile("s_waitcnt vmcnt(" #n ")" ::: "memory")
; #define PG8_WAIT_L(n) asm volatile("s_waitcnt lgkmcnt(" #n ")" ::: "memory")
; #define PG8_BAR __builtin_amdgcn_s_barrier()
; #define PG8_SCHED __builtin_amdgcn_sched_barrier(0)
; template <class Epi, class Sched, bool ALIGN_EPI = false, bool SP2 = false>
; __device__ __forceinline__ void gemm_phase(PG8_LAS unsigned char* lds, const Gemm g, const Sched& S, const Epi& E, int wave_s) {
;     ...
;             PG8_LDB(B0, 0, 0); PG8_LDB(B1, 0, 1); PG8_SCHED; PG8_LDA(At, 0, 0); PG8_STAGE(PG8_SA(1, 1), a1 + hstep, voffA);
;             PG8_WAIT_V(8); PG8_WAIT_L(0); PG8_BAR; PG8_MMA(0, 0, At, B0); PG8_MMA(0, 1, At, B1); PG8_BAR; PG8_SCHED;
;             PG8_LDA(At, 0, 1); PG8_STAGE(PG8_SB(0, 0), b2, voffB); PG8_STAGE(PG8_SB(0, 1), b2 + hstep, voffB); PG8_STAGE(PG8_SA(0, 0), a2, voffA);
;             PG8_WAIT_V(8); PG8_WAIT_L(0); PG8_BAR; PG8_MMA(1, 0, At, B0); PG8_MMA(1, 1, At, B1); PG8_BAR; PG8_SCHED;
.LBB0_1343:
	s_add_u32 s46, s44, 0xfff00080
	s_addc_u32 s47, s45, -1
	s_cmp_eq_u32 s88, 60
	s_cselect_b32 s49, s29, s47
	s_cselect_b32 s48, s74, s46
	s_cselect_b32 s47, s35, s87
	s_cselect_b32 s46, s75, s86
	s_mov_b32 m0, s76
	s_nop 0
	global_load_lds_dwordx4 v138, s[44:45]
	s_mov_b32 m0, s77
	s_nop 0
	global_load_lds_dwordx4 v140, s[44:45]
	ds_read_b128 v[144:147], v150 offset:3072
	ds_read_b128 v[152:155], v150 offset:2048
	ds_read_b128 v[156:159], v150 offset:1024
	ds_read_b128 v[160:163], v150
	ds_read_b128 v[164:167], v149 offset:3072
	ds_read_b128 v[168:171], v149 offset:2048
	ds_read_b128 v[172:175], v149 offset:1024
	ds_read_b128 v[176:179], v149
	ds_read_b128 v[180:183], v151
	ds_read_b128 v[184:187], v151 offset:1024
	ds_read_b128 v[188:191], v151 offset:2048
	ds_read_b128 v[192:195], v151 offset:3072
	ds_read_b128 v[196:199], v151 offset:4096
	ds_read_b128 v[200:203], v151 offset:5120
	ds_read_b128 v[204:207], v151 offset:6144
	ds_read_b128 v[208:211], v151 offset:7168
	s_waitcnt vmcnt(8)
	s_waitcnt lgkmcnt(0)
	s_barrier
	v_mfma_f32_16x16x32_bf16 v[124:127], v[176:179], v[180:183], v[124:127]
	v_mfma_f32_16x16x32_bf16 v[124:127], v[172:175], v[184:187], v[124:127]
	v_mfma_f32_16x16x32_bf16 v[120:123], v[164:167], v[184:187], v[120:123]
	v_mfma_f32_16x16x32_bf16 v[120:123], v[168:171], v[180:183], v[120:123]
	v_mfma_f32_16x16x32_bf16 v[104:107], v[168:171], v[188:191], v[104:107]
	v_mfma_f32_16x16x32_bf16 v[104:107], v[164:167], v[192:195], v[104:107]
	v_mfma_f32_16x16x32_bf16 v[108:111], v[172:175], v[192:195], v[108:111]
	v_mfma_f32_16x16x32_bf16 v[108:111], v[176:179], v[188:191], v[108:111]
	v_mfma_f32_16x16x32_bf16 v[92:95], v[176:179], v[196:199], v[92:95]
	v_mfma_f32_16x16x32_bf16 v[92:95], v[172:175], v[200:203], v[92:95]
	v_mfma_f32_16x16x32_bf16 v[88:91], v[164:167], v[200:203], v[88:91]
	v_mfma_f32_16x16x32_bf16 v[88:91], v[168:171], v[196:199], v[88:91]
	v_mfma_f32_16x16x32_bf16 v[72:75], v[168:171], v[204:207], v[72:75]
	v_mfma_f32_16x16x32_bf16 v[72:75], v[164:167], v[208:211], v[72:75]
	v_mfma_f32_16x16x32_bf16 v[76:79], v[172:175], v[208:211], v[76:79]
	v_mfma_f32_16x16x32_bf16 v[76:79], v[176:179], v[204:207], v[76:79]
	v_mfma_f32_16x16x32_bf16 v[116:119], v[160:163], v[180:183], v[116:119]
	v_mfma_f32_16x16x32_bf16 v[116:119], v[156:159], v[184:187], v[116:119]
	v_mfma_f32_16x16x32_bf16 v[112:115], v[144:147], v[184:187], v[112:115]
	v_mfma_f32_16x16x32_bf16 v[112:115], v[152:155], v[180:183], v[112:115]
	v_mfma_f32_16x16x32_bf16 v[96:99], v[152:155], v[188:191], v[96:99]
	v_mfma_f32_16x16x32_bf16 v[96:99], v[144:147], v[192:195], v[96:99]
	v_mfma_f32_16x16x32_bf16 v[100:103], v[156:159], v[192:195], v[100:103]
	v_mfma_f32_16x16x32_bf16 v[100:103], v[160:163], v[188:191], v[100:103]
	v_mfma_f32_16x16x32_bf16 v[84:87], v[160:163], v[196:199], v[84:87]
	v_mfma_f32_16x16x32_bf16 v[84:87], v[156:159], v[200:203], v[84:87]
	v_mfma_f32_16x16x32_bf16 v[80:83], v[144:147], v[200:203], v[80:83]
	v_mfma_f32_16x16x32_bf16 v[80:83], v[152:155], v[196:199], v[80:83]
	v_mfma_f32_16x16x32_bf16 v[64:67], v[152:155], v[204:207], v[64:67]
	v_mfma_f32_16x16x32_bf16 v[64:67], v[144:147], v[208:211], v[64:67]
	v_mfma_f32_16x16x32_bf16 v[68:71], v[156:159], v[208:211], v[68:71]
	v_mfma_f32_16x16x32_bf16 v[68:71], v[160:163], v[204:207], v[68:71]
	s_barrier
	s_mov_b32 m0, s78
	s_nop 0
	s_add_u32 s90, s46, 0x100000
	global_load_lds_dwordx4 v132, s[46:47]
	s_mov_b32 m0, s79
	s_addc_u32 s91, s47, 0
	global_load_lds_dwordx4 v128, s[46:47]
	s_mov_b32 m0, s80
	s_nop 0
	global_load_lds_dwordx4 v132, s[90:91]
	s_mov_b32 m0, s81
	s_nop 0
	global_load_lds_dwordx4 v128, s[90:91]
	s_mov_b32 m0, s41
	s_nop 0
	global_load_lds_dwordx4 v134, s[48:49]
	s_mov_b32 m0, s43
	s_nop 0
	global_load_lds_dwordx4 v130, s[48:49]
	ds_read_b128 v[180:183], v151 offset:16384
	ds_read_b128 v[184:187], v151 offset:17408
	ds_read_b128 v[188:191], v151 offset:18432
	ds_read_b128 v[192:195], v151 offset:19456
	ds_read_b128 v[196:199], v151 offset:20480
	ds_read_b128 v[200:203], v151 offset:21504
	ds_read_b128 v[204:207], v151 offset:22528
	ds_read_b128 v[208:211], v151 offset:23552
	s_waitcnt vmcnt(8)
	s_waitcnt lgkmcnt(0)
	s_barrier
	v_mfma_f32_16x16x32_bf16 v[60:63], v[176:179], v[180:183], v[60:63]
	v_mfma_f32_16x16x32_bf16 v[60:63], v[172:175], v[184:187], v[60:63]
	v_mfma_f32_16x16x32_bf16 v[56:59], v[164:167], v[184:187], v[56:59]
	v_mfma_f32_16x16x32_bf16 v[56:59], v[168:171], v[180:183], v[56:59]
	v_mfma_f32_16x16x32_bf16 v[40:43], v[168:171], v[188:191], v[40:43]
	v_mfma_f32_16x16x32_bf16 v[40:43], v[164:167], v[192:195], v[40:43]
	v_mfma_f32_16x16x32_bf16 v[44:47], v[172:175], v[192:195], v[44:47]
	v_mfma_f32_16x16x32_bf16 v[44:47], v[176:179], v[188:191], v[44:47]
	v_mfma_f32_16x16x32_bf16 v[28:31], v[176:179], v[196:199], v[28:31]
	v_mfma_f32_16x16x32_bf16 v[28:31], v[172:175], v[200:203], v[28:31]
	v_mfma_f32_16x16x32_bf16 v[24:27], v[164:167], v[200:203], v[24:27]
	v_mfma_f32_16x16x32_bf16 v[24:27], v[168:171], v[196:199], v[24:27]
	v_mfma_f32_16x16x32_bf16 v[8:11], v[168:171], v[204:207], v[8:11]
	v_mfma_f32_16x16x32_bf16 v[8:11], v[164:167], v[208:211], v[8:11]
	v_mfma_f32_16x16x32_bf16 v[12:15], v[172:175], v[208:211], v[12:15]
	v_mfma_f32_16x16x32_bf16 v[12:15], v[176:179], v[204:207], v[12:15]
	v_mfma_f32_16x16x32_bf16 v[52:55], v[160:163], v[180:183], v[52:55]
	v_mfma_f32_16x16x32_bf16 v[52:55], v[156:159], v[184:187], v[52:55]
	v_mfma_f32_16x16x32_bf16 v[48:51], v[144:147], v[184:187], v[48:51]
	v_mfma_f32_16x16x32_bf16 v[48:51], v[152:155], v[180:183], v[48:51]
	v_mfma_f32_16x16x32_bf16 v[32:35], v[152:155], v[188:191], v[32:35]
	v_mfma_f32_16x16x32_bf16 v[32:35], v[144:147], v[192:195], v[32:35]
	v_mfma_f32_16x16x32_bf16 v[36:39], v[156:159], v[192:195], v[36:39]
	v_mfma_f32_16x16x32_bf16 v[36:39], v[160:163], v[188:191], v[36:39]
	v_mfma_f32_16x16x32_bf16 v[20:23], v[160:163], v[196:199], v[20:23]
	v_mfma_f32_16x16x32_bf16 v[20:23], v[156:159], v[200:203], v[20:23]
	v_mfma_f32_16x16x32_bf16 v[16:19], v[144:147], v[200:203], v[16:19]
	v_mfma_f32_16x16x32_bf16 v[16:19], v[152:155], v[196:199], v[16:19]
	v_mfma_f32_16x16x32_bf16 v[0:3], v[152:155], v[204:207], v[0:3]
	v_mfma_f32_16x16x32_bf16 v[0:3], v[144:147], v[208:211], v[0:3]
	v_mfma_f32_16x16x32_bf16 v[4:7], v[156:159], v[208:211], v[4:7]
	v_mfma_f32_16x16x32_bf16 v[4:7], v[160:163], v[204:207], v[4:7]
	s_barrier
; #define PG8_STAGE(bufoff, gbase, voff) do { _Pragma("unroll") for (int _i = 0; _i < 2; ++_i) \
;         __builtin_amdgcn_global_load_lds((const unsigned*)((const char*)(gbase) + (voff)[_i]), (PG8_LAS unsigned*)(lds + (bufoff) + ldsw + _i * 8192), 16, 0, 0); } while (0)
; #define PG8_LDA(dst, b, h) do { _Pragma("unroll") for (int m = 0; m < 4; ++m) _Pragma("unroll") for (int k = 0; k < 2; ++k) dst[m][k] = *(const PG8_LAS bf16x8*)(lds + PG8_SA(b, h) + aoff + m * 2048 + k * 1024); } while (0)
; #define PG8_LDB(dst, b, h) do { _Pragma("unroll") for (int n = 0; n < 2; ++n) _Pragma("unroll") for (int k = 0; k < 2; ++k) dst[n][k] = *(const PG8_LAS bf16x8*)(lds + PG8_SB(b, h) + boff + n * 2048 + k * 1024); } while (0)
; #define PG8_MMA(ai, bj, At, Bt) do { __builtin_amdgcn_s_setprio(1); _Pragma("unroll") for (int m = 0; m < 4; ++m) _Pragma("unroll") for (int n = 0; n < 2; ++n) _Pragma("unroll") for (int k = 0; k < 2; ++k) \
;         acc[ai][bj][m][n] = __builtin_amdgcn_mfma_f32_16x16x32_bf16(Bt[n][k], At[m][k], acc[ai][bj][m][n], 0, 0, 0); __builtin_amdgcn_s_setprio(0); } while (0)
; #define PG8_WAIT_V(n) asm volatile("s_waitcnt vmcnt(" #n ")" ::: "memory")
; #define PG8_WAIT_L(n) asm volatile("s_waitcnt lgkmcnt(" #n ")" ::: "memory")
; #define PG8_BAR __builtin_amdgcn_s_barrier()
; #define PG8_SCHED __builtin_amdgcn_sched_barrier(0)
; template <class Epi, class Sched, bool ALIGN_EPI = false, bool SP2 = false>
; __device__ __forceinline__ void gemm_phase(PG8_LAS unsigned char* lds, const Gemm g, const Sched& S, const Epi& E, int wave_s) {
;     ...
;             PG8_LDB(B0, 1, 0); PG8_LDB(B1, 1, 1); PG8_SCHED; PG8_LDA(At, 1, 0); PG8_STAGE(PG8_SA(0, 1), a2 + hstep, voffA);
;             PG8_WAIT_V(8); PG8_WAIT_L(0); PG8_BAR; PG8_MMA(0, 0, At, B0); PG8_MMA(0, 1, At, B1); PG8_BAR; PG8_SCHED;
;             PG8_LDA(At, 1, 1); PG8_STAGE(PG8_SB(1, 0), b3, voffB); PG8_STAGE(PG8_SB(1, 1), b3 + hstep, voffB); PG8_STAGE(PG8_SA(1, 0), a3, voffA);
;             PG8_WAIT_V(8); PG8_WAIT_L(0); PG8_BAR; PG8_MMA(1, 0, At, B0); PG8_MMA(1, 1, At, B1); PG8_BAR; PG8_SCHED;
	s_add_u32 s48, s48, 0x100000
	s_addc_u32 s49, s49, 0
	s_mov_b32 m0, s58
	s_nop 0
	global_load_lds_dwordx4 v134, s[48:49]
	s_mov_b32 m0, s59
	s_nop 0
	global_load_lds_dwordx4 v130, s[48:49]
	ds_read_b128 v[144:147], v142
	ds_read_b128 v[152:155], v142 offset:1024
	ds_read_b128 v[156:159], v142 offset:2048
	ds_read_b128 v[160:163], v142 offset:3072
	ds_read_b128 v[164:167], v143
	ds_read_b128 v[168:171], v143 offset:1024
	ds_read_b128 v[172:175], v143 offset:2048
	ds_read_b128 v[176:179], v143 offset:3072
	ds_read_b128 v[180:183], v151 offset:32768
	ds_read_b128 v[184:187], v151 offset:33792
	ds_read_b128 v[188:191], v151 offset:34816
	ds_read_b128 v[192:195], v151 offset:35840
	ds_read_b128 v[196:199], v151 offset:36864
	ds_read_b128 v[200:203], v151 offset:37888
	ds_read_b128 v[204:207], v151 offset:38912
	ds_read_b128 v[208:211], v151 offset:39936
	s_waitcnt vmcnt(8)
	s_waitcnt lgkmcnt(0)
	s_barrier
	v_mfma_f32_16x16x32_bf16 v[124:127], v[144:147], v[180:183], v[124:127]
	v_mfma_f32_16x16x32_bf16 v[124:127], v[152:155], v[184:187], v[124:127]
	v_mfma_f32_16x16x32_bf16 v[120:123], v[160:163], v[184:187], v[120:123]
	v_mfma_f32_16x16x32_bf16 v[120:123], v[156:159], v[180:183], v[120:123]
	v_mfma_f32_16x16x32_bf16 v[104:107], v[156:159], v[188:191], v[104:107]
	v_mfma_f32_16x16x32_bf16 v[104:107], v[160:163], v[192:195], v[104:107]
	v_mfma_f32_16x16x32_bf16 v[108:111], v[152:155], v[192:195], v[108:111]
	v_mfma_f32_16x16x32_bf16 v[108:111], v[144:147], v[188:191], v[108:111]
	v_mfma_f32_16x16x32_bf16 v[92:95], v[144:147], v[196:199], v[92:95]
	v_mfma_f32_16x16x32_bf16 v[92:95], v[152:155], v[200:203], v[92:95]
	v_mfma_f32_16x16x32_bf16 v[88:91], v[160:163], v[200:203], v[88:91]
	v_mfma_f32_16x16x32_bf16 v[88:91], v[156:159], v[196:199], v[88:91]
	v_mfma_f32_16x16x32_bf16 v[72:75], v[156:159], v[204:207], v[72:75]
	v_mfma_f32_16x16x32_bf16 v[72:75], v[160:163], v[208:211], v[72:75]
	v_mfma_f32_16x16x32_bf16 v[76:79], v[152:155], v[208:211], v[76:79]
	v_mfma_f32_16x16x32_bf16 v[76:79], v[144:147], v[204:207], v[76:79]
	v_mfma_f32_16x16x32_bf16 v[116:119], v[164:167], v[180:183], v[116:119]
	v_mfma_f32_16x16x32_bf16 v[116:119], v[168:171], v[184:187], v[116:119]
	v_mfma_f32_16x16x32_bf16 v[112:115], v[176:179], v[184:187], v[112:115]
	v_mfma_f32_16x16x32_bf16 v[112:115], v[172:175], v[180:183], v[112:115]
	v_mfma_f32_16x16x32_bf16 v[96:99], v[172:175], v[188:191], v[96:99]
	v_mfma_f32_16x16x32_bf16 v[96:99], v[176:179], v[192:195], v[96:99]
	v_mfma_f32_16x16x32_bf16 v[100:103], v[168:171], v[192:195], v[100:103]
	v_mfma_f32_16x16x32_bf16 v[100:103], v[164:167], v[188:191], v[100:103]
	v_mfma_f32_16x16x32_bf16 v[84:87], v[164:167], v[196:199], v[84:87]
	v_mfma_f32_16x16x32_bf16 v[84:87], v[168:171], v[200:203], v[84:87]
	v_mfma_f32_16x16x32_bf16 v[80:83], v[176:179], v[200:203], v[80:83]
	v_mfma_f32_16x16x32_bf16 v[80:83], v[172:175], v[196:199], v[80:83]
	v_mfma_f32_16x16x32_bf16 v[64:67], v[172:175], v[204:207], v[64:67]
	v_mfma_f32_16x16x32_bf16 v[64:67], v[176:179], v[208:211], v[64:67]
	v_mfma_f32_16x16x32_bf16 v[68:71], v[168:171], v[208:211], v[68:71]
	v_mfma_f32_16x16x32_bf16 v[68:71], v[164:167], v[204:207], v[68:71]
	s_barrier
	s_mov_b32 m0, s82
	s_nop 0
	s_add_u32 s94, s46, 0x80
	s_addc_u32 s95, s47, 0
	s_add_u32 s46, s46, 0x100080
	global_load_lds_dwordx4 v132, s[94:95]
	s_mov_b32 m0, s83
	s_addc_u32 s47, s47, 0
	global_load_lds_dwordx4 v128, s[94:95]
	s_mov_b32 m0, s84
	s_nop 0
	global_load_lds_dwordx4 v132, s[46:47]
	s_mov_b32 m0, s85
	s_nop 0
	global_load_lds_dwordx4 v128, s[46:47]
	s_mov_b32 m0, s62
	s_nop 0
	s_add_u32 s96, s48, 0xfff00080
	s_addc_u32 s97, s49, -1
	global_load_lds_dwordx4 v134, s[96:97]
	s_mov_b32 m0, s63
	s_nop 0
	global_load_lds_dwordx4 v130, s[96:97]
	ds_read_b128 v[180:183], v151 offset:49152
	ds_read_b128 v[184:187], v151 offset:50176
	ds_read_b128 v[188:191], v151 offset:51200
	ds_read_b128 v[192:195], v151 offset:52224
	ds_read_b128 v[196:199], v151 offset:53248
	ds_read_b128 v[200:203], v151 offset:54272
	ds_read_b128 v[204:207], v151 offset:55296
	ds_read_b128 v[208:211], v151 offset:56320
	s_waitcnt vmcnt(8)
	s_waitcnt lgkmcnt(0)
	s_barrier
	v_mfma_f32_16x16x32_bf16 v[60:63], v[144:147], v[180:183], v[60:63]
	v_mfma_f32_16x16x32_bf16 v[60:63], v[152:155], v[184:187], v[60:63]
	v_mfma_f32_16x16x32_bf16 v[56:59], v[160:163], v[184:187], v[56:59]
	v_mfma_f32_16x16x32_bf16 v[56:59], v[156:159], v[180:183], v[56:59]
	v_mfma_f32_16x16x32_bf16 v[40:43], v[156:159], v[188:191], v[40:43]
	v_mfma_f32_16x16x32_bf16 v[40:43], v[160:163], v[192:195], v[40:43]
	v_mfma_f32_16x16x32_bf16 v[44:47], v[152:155], v[192:195], v[44:47]
	v_mfma_f32_16x16x32_bf16 v[44:47], v[144:147], v[188:191], v[44:47]
	v_mfma_f32_16x16x32_bf16 v[28:31], v[144:147], v[196:199], v[28:31]
	v_mfma_f32_16x16x32_bf16 v[28:31], v[152:155], v[200:203], v[28:31]
	v_mfma_f32_16x16x32_bf16 v[24:27], v[160:163], v[200:203], v[24:27]
	v_mfma_f32_16x16x32_bf16 v[24:27], v[156:159], v[196:199], v[24:27]
	v_mfma_f32_16x16x32_bf16 v[8:11], v[156:159], v[204:207], v[8:11]
	v_mfma_f32_16x16x32_bf16 v[8:11], v[160:163], v[208:211], v[8:11]
	v_mfma_f32_16x16x32_bf16 v[12:15], v[152:155], v[208:211], v[12:15]
	v_mfma_f32_16x16x32_bf16 v[12:15], v[144:147], v[204:207], v[12:15]
	v_mfma_f32_16x16x32_bf16 v[52:55], v[164:167], v[180:183], v[52:55]
	v_mfma_f32_16x16x32_bf16 v[52:55], v[168:171], v[184:187], v[52:55]
	v_mfma_f32_16x16x32_bf16 v[48:51], v[176:179], v[184:187], v[48:51]
	v_mfma_f32_16x16x32_bf16 v[48:51], v[172:175], v[180:183], v[48:51]
	v_mfma_f32_16x16x32_bf16 v[32:35], v[172:175], v[188:191], v[32:35]
	v_mfma_f32_16x16x32_bf16 v[32:35], v[176:179], v[192:195], v[32:35]
	v_mfma_f32_16x16x32_bf16 v[36:39], v[168:171], v[192:195], v[36:39]
	v_mfma_f32_16x16x32_bf16 v[36:39], v[164:167], v[188:191], v[36:39]
	v_mfma_f32_16x16x32_bf16 v[20:23], v[164:167], v[196:199], v[20:23]
	v_mfma_f32_16x16x32_bf16 v[20:23], v[168:171], v[200:203], v[20:23]
	v_mfma_f32_16x16x32_bf16 v[16:19], v[176:179], v[200:203], v[16:19]
	v_mfma_f32_16x16x32_bf16 v[16:19], v[172:175], v[196:199], v[16:19]
	v_mfma_f32_16x16x32_bf16 v[0:3], v[172:175], v[204:207], v[0:3]
	v_mfma_f32_16x16x32_bf16 v[0:3], v[176:179], v[208:211], v[0:3]
	v_mfma_f32_16x16x32_bf16 v[4:7], v[168:171], v[208:211], v[4:7]
	v_mfma_f32_16x16x32_bf16 v[4:7], v[164:167], v[204:207], v[4:7]
	s_barrier
	s_add_i32 s88, s88, 2
	s_add_u32 s44, s44, 0x100
	s_addc_u32 s45, s45, 0
	s_add_u32 s86, s86, 0x100
	s_addc_u32 s87, s87, 0
	s_cmp_gt_u32 s88, 61
	s_cbranch_scc0 .LBB0_1343
	s_and_b64 vcc, exec, s[14:15]
	s_cbranch_vccz .LBB0_1346
	s_barrier

; #define PG8_LAS __attribute__((address_space(3)))
; #define PG8_STAGE(bufoff, gbase, voff) do { _Pragma("unroll") for (int _i = 0; _i < 2; ++_i) \
;         __builtin_amdgcn_global_load_lds((const unsigned*)((const char*)(gbase) + (voff)[_i]), (PG8_LAS unsigned*)(lds + (bufoff) + ldsw + _i * 8192), 16, 0, 0); } while (0)
; #define PG8_LDA(dst, b, h) do { _Pragma("unroll") for (int m = 0; m < 4; ++m) _Pragma("unroll") for (int k = 0; k < 2; ++k) dst[m][k] = *(const PG8_LAS bf16x8*)(lds + PG8_SA(b, h) + aoff + m * 2048 + k * 1024); } while (0)
; #define PG8_LDB(dst, b, h) do { _Pragma("unroll") for (int n = 0; n < 2; ++n) _Pragma("unroll") for (int k = 0; k < 2; ++k) dst[n][k] = *(const PG8_LAS bf16x8*)(lds + PG8_SB(b, h) + boff + n * 2048 + k * 1024); } while (0)
; #define PG8_WAIT_V(n) asm volatile("s_waitcnt vmcnt(" #n ")" ::: "memory")
; #define PG8_WAIT_L(n) asm volatile("s_waitcnt lgkmcnt(" #n ")" ::: "memory")
; #define PG8_BAR __builtin_amdgcn_s_barrier()
; #define PG8_SCHED __builtin_amdgcn_sched_barrier(0)
; template <class Epi, class Sched, bool ALIGN_EPI = false, bool SP2 = false>
; __device__ __forceinline__ void gemm_phase(PG8_LAS unsigned char* lds, const Gemm g, const Sched& S, const Epi& E, int wave_s) {
;     ...
;             const bool last = (t == nt - 2);
;             if constexpr (Epi::NEED_RS) { if (t == 0 && wid < 4) __builtin_amdgcn_global_load_lds((const unsigned*)(E.rstd + cur.pm * BM + wid * 64 + lane), (PG8_LAS unsigned*)(rsl + wid * 64), 4, 0, 0); }
;             const char* a1 = cA + (size_t)(t + 1) * kstep;
;             const char* a2 = last ? nA : cA + (size_t)(t + 2) * kstep; const char* b2 = last ? nB : cB + (size_t)(t + 2) * kstep;
;             const char* a3 = a2 + kstep; const char* b3 = b2 + kstep;
;             if (last && has_next) S.a_ready(nxt);
;             if constexpr (SP2) {
;             PG8_LDB(B0, 0, 0); PG8_LDB(B1, 0, 1); PG8_SCHED; PG8_LDA(At, 0, 0); PG8_STAGE(PG8_SA(1, 1), a1 + hstep, voffA);
;             PG8_WAIT_V(8); PG8_WAIT_L(0); PG8_BAR; PG8_MMA(0, 0, At, B0); PG8_MMA(0, 1, At, B1); PG8_BAR; PG8_SCHED;
;             PG8_LDA(At, 0, 1); PG8_STAGE(PG8_SB(0, 0), b2, voffB); PG8_STAGE(PG8_SB(0, 1), b2 + hstep, voffB); PG8_STAGE(PG8_SA(0, 0), a2, voffA);
;             PG8_WAIT_V(8); PG8_WAIT_L(0); PG8_BAR; PG8_MMA(1, 0, At, B0); PG8_MMA(1, 1, At, B1); PG8_BAR; PG8_SCHED;
.LBB0_1410:
	s_add_u32 s45, s50, 0xffc00080
	s_addc_u32 s52, s51, -1
	s_cmp_eq_u32 s85, s43
	s_cselect_b32 s55, s47, s52
	s_cselect_b32 s54, s46, s45
	s_cselect_b32 s53, s49, s41
	s_cselect_b32 s52, s48, s7
	s_add_i32 m0, s9, 0xc000
	s_nop 0
	global_load_lds_dwordx4 v192, s[50:51]
	s_add_i32 m0, s9, 0xe000
	s_nop 0
	global_load_lds_dwordx4 v194, s[50:51]
	ds_read_b128 v[128:131], v211
	ds_read_b128 v[132:135], v211 offset:1024
	ds_read_b128 v[136:139], v211 offset:2048
	ds_read_b128 v[140:143], v211 offset:3072
	ds_read_b128 v[144:147], v212
	ds_read_b128 v[148:151], v212 offset:1024
	ds_read_b128 v[152:155], v212 offset:2048
	ds_read_b128 v[156:159], v212 offset:3072
	ds_read_b128 v[160:163], v213
	ds_read_b128 v[164:167], v213 offset:1024
	ds_read_b128 v[168:171], v213 offset:2048
	ds_read_b128 v[172:175], v213 offset:3072
	ds_read_b128 v[176:179], v213 offset:4096
	ds_read_b128 v[180:183], v213 offset:5120
	ds_read_b128 v[196:199], v213 offset:6144
	ds_read_b128 v[200:203], v213 offset:7168
	s_waitcnt vmcnt(8)
	s_waitcnt lgkmcnt(0)
	s_barrier
	v_mfma_f32_16x16x32_bf16 v[124:127], v[128:131], v[160:163], v[124:127]
	v_mfma_f32_16x16x32_bf16 v[124:127], v[132:135], v[164:167], v[124:127]
	v_mfma_f32_16x16x32_bf16 v[120:123], v[140:143], v[164:167], v[120:123]
	v_mfma_f32_16x16x32_bf16 v[120:123], v[136:139], v[160:163], v[120:123]
	v_mfma_f32_16x16x32_bf16 v[104:107], v[136:139], v[168:171], v[104:107]
	v_mfma_f32_16x16x32_bf16 v[104:107], v[140:143], v[172:175], v[104:107]
	v_mfma_f32_16x16x32_bf16 v[108:111], v[132:135], v[172:175], v[108:111]
	v_mfma_f32_16x16x32_bf16 v[108:111], v[128:131], v[168:171], v[108:111]
	v_mfma_f32_16x16x32_bf16 v[92:95], v[128:131], v[176:179], v[92:95]
	v_mfma_f32_16x16x32_bf16 v[92:95], v[132:135], v[180:183], v[92:95]
	v_mfma_f32_16x16x32_bf16 v[88:91], v[140:143], v[180:183], v[88:91]
	v_mfma_f32_16x16x32_bf16 v[88:91], v[136:139], v[176:179], v[88:91]
	v_mfma_f32_16x16x32_bf16 v[72:75], v[136:139], v[196:199], v[72:75]
	v_mfma_f32_16x16x32_bf16 v[72:75], v[140:143], v[200:203], v[72:75]
	v_mfma_f32_16x16x32_bf16 v[76:79], v[132:135], v[200:203], v[76:79]
	v_mfma_f32_16x16x32_bf16 v[76:79], v[128:131], v[196:199], v[76:79]
	v_mfma_f32_16x16x32_bf16 v[116:119], v[144:147], v[160:163], v[116:119]
	v_mfma_f32_16x16x32_bf16 v[116:119], v[148:151], v[164:167], v[116:119]
	v_mfma_f32_16x16x32_bf16 v[112:115], v[156:159], v[164:167], v[112:115]
	v_mfma_f32_16x16x32_bf16 v[112:115], v[152:155], v[160:163], v[112:115]
	v_mfma_f32_16x16x32_bf16 v[96:99], v[152:155], v[168:171], v[96:99]
	v_mfma_f32_16x16x32_bf16 v[96:99], v[156:159], v[172:175], v[96:99]
	v_mfma_f32_16x16x32_bf16 v[100:103], v[148:151], v[172:175], v[100:103]
	v_mfma_f32_16x16x32_bf16 v[100:103], v[144:147], v[168:171], v[100:103]
	v_mfma_f32_16x16x32_bf16 v[84:87], v[144:147], v[176:179], v[84:87]
	v_mfma_f32_16x16x32_bf16 v[84:87], v[148:151], v[180:183], v[84:87]
	v_mfma_f32_16x16x32_bf16 v[80:83], v[156:159], v[180:183], v[80:83]
	v_mfma_f32_16x16x32_bf16 v[80:83], v[152:155], v[176:179], v[80:83]
	v_mfma_f32_16x16x32_bf16 v[64:67], v[152:155], v[196:199], v[64:67]
	v_mfma_f32_16x16x32_bf16 v[64:67], v[156:159], v[200:203], v[64:67]
	v_mfma_f32_16x16x32_bf16 v[68:71], v[148:151], v[200:203], v[68:71]
	v_mfma_f32_16x16x32_bf16 v[68:71], v[144:147], v[196:199], v[68:71]
	s_barrier
	s_add_i32 s45, s75, s60
	s_mov_b32 m0, s45
	s_nop 0
	global_load_lds_dwordx4 v186, s[52:53]
	s_add_i32 m0, s45, 0x2000
	s_add_u32 s86, s52, 0x400000
	s_addc_u32 s87, s53, 0
	s_add_i32 s45, s76, s60
	global_load_lds_dwordx4 v190, s[52:53]
	s_mov_b32 m0, s45
	s_nop 0
	global_load_lds_dwordx4 v186, s[86:87]
	s_add_i32 m0, s45, 0x2000
	s_nop 0
	global_load_lds_dwordx4 v190, s[86:87]
	s_mov_b32 m0, s9
	s_nop 0
	global_load_lds_dwordx4 v184, s[54:55]
	s_mov_b32 m0, s61
	s_nop 0
	global_load_lds_dwordx4 v188, s[54:55]
	ds_read_b128 v[160:163], v213 offset:16384
	ds_read_b128 v[164:167], v213 offset:17408
	ds_read_b128 v[168:171], v213 offset:18432
	ds_read_b128 v[172:175], v213 offset:19456
	ds_read_b128 v[176:179], v213 offset:20480
	ds_read_b128 v[180:183], v213 offset:21504
	ds_read_b128 v[196:199], v213 offset:22528
	ds_read_b128 v[200:203], v213 offset:23552
	s_waitcnt vmcnt(8)
	s_waitcnt lgkmcnt(0)
	s_barrier
	v_mfma_f32_16x16x32_bf16 v[60:63], v[128:131], v[160:163], v[60:63]
	v_mfma_f32_16x16x32_bf16 v[60:63], v[132:135], v[164:167], v[60:63]
	v_mfma_f32_16x16x32_bf16 v[56:59], v[140:143], v[164:167], v[56:59]
	v_mfma_f32_16x16x32_bf16 v[56:59], v[136:139], v[160:163], v[56:59]
	v_mfma_f32_16x16x32_bf16 v[40:43], v[136:139], v[168:171], v[40:43]
	v_mfma_f32_16x16x32_bf16 v[40:43], v[140:143], v[172:175], v[40:43]
	v_mfma_f32_16x16x32_bf16 v[44:47], v[132:135], v[172:175], v[44:47]
	v_mfma_f32_16x16x32_bf16 v[44:47], v[128:131], v[168:171], v[44:47]
	v_mfma_f32_16x16x32_bf16 v[28:31], v[128:131], v[176:179], v[28:31]
	v_mfma_f32_16x16x32_bf16 v[28:31], v[132:135], v[180:183], v[28:31]
	v_mfma_f32_16x16x32_bf16 v[24:27], v[140:143], v[180:183], v[24:27]
	v_mfma_f32_16x16x32_bf16 v[24:27], v[136:139], v[176:179], v[24:27]
	v_mfma_f32_16x16x32_bf16 v[8:11], v[136:139], v[196:199], v[8:11]
	v_mfma_f32_16x16x32_bf16 v[8:11], v[140:143], v[200:203], v[8:11]
	v_mfma_f32_16x16x32_bf16 v[12:15], v[132:135], v[200:203], v[12:15]
	v_mfma_f32_16x16x32_bf16 v[12:15], v[128:131], v[196:199], v[12:15]
	v_mfma_f32_16x16x32_bf16 v[52:55], v[144:147], v[160:163], v[52:55]
	v_mfma_f32_16x16x32_bf16 v[52:55], v[148:151], v[164:167], v[52:55]
	v_mfma_f32_16x16x32_bf16 v[48:51], v[156:159], v[164:167], v[48:51]
	v_mfma_f32_16x16x32_bf16 v[48:51], v[152:155], v[160:163], v[48:51]
	v_mfma_f32_16x16x32_bf16 v[32:35], v[152:155], v[168:171], v[32:35]
	v_mfma_f32_16x16x32_bf16 v[32:35], v[156:159], v[172:175], v[32:35]
	v_mfma_f32_16x16x32_bf16 v[36:39], v[148:151], v[172:175], v[36:39]
	v_mfma_f32_16x16x32_bf16 v[36:39], v[144:147], v[168:171], v[36:39]
	v_mfma_f32_16x16x32_bf16 v[20:23], v[144:147], v[176:179], v[20:23]
	v_mfma_f32_16x16x32_bf16 v[20:23], v[148:151], v[180:183], v[20:23]
	v_mfma_f32_16x16x32_bf16 v[16:19], v[156:159], v[180:183], v[16:19]
	v_mfma_f32_16x16x32_bf16 v[16:19], v[152:155], v[176:179], v[16:19]
	v_mfma_f32_16x16x32_bf16 v[0:3], v[152:155], v[196:199], v[0:3]
	v_mfma_f32_16x16x32_bf16 v[0:3], v[156:159], v[200:203], v[0:3]
	v_mfma_f32_16x16x32_bf16 v[4:7], v[148:151], v[200:203], v[4:7]
	v_mfma_f32_16x16x32_bf16 v[4:7], v[144:147], v[196:199], v[4:7]
	s_barrier
; #define PG8_STAGE(bufoff, gbase, voff) do { _Pragma("unroll") for (int _i = 0; _i < 2; ++_i) \
;         __builtin_amdgcn_global_load_lds((const unsigned*)((const char*)(gbase) + (voff)[_i]), (PG8_LAS unsigned*)(lds + (bufoff) + ldsw + _i * 8192), 16, 0, 0); } while (0)
; #define PG8_LDA(dst, b, h) do { _Pragma("unroll") for (int m = 0; m < 4; ++m) _Pragma("unroll") for (int k = 0; k < 2; ++k) dst[m][k] = *(const PG8_LAS bf16x8*)(lds + PG8_SA(b, h) + aoff + m * 2048 + k * 1024); } while (0)
; #define PG8_LDB(dst, b, h) do { _Pragma("unroll") for (int n = 0; n < 2; ++n) _Pragma("unroll") for (int k = 0; k < 2; ++k) dst[n][k] = *(const PG8_LAS bf16x8*)(lds + PG8_SB(b, h) + boff + n * 2048 + k * 1024); } while (0)
; #define PG8_MMA(ai, bj, At, Bt) do { __builtin_amdgcn_s_setprio(1); _Pragma("unroll") for (int m = 0; m < 4; ++m) _Pragma("unroll") for (int n = 0; n < 2; ++n) _Pragma("unroll") for (int k = 0; k < 2; ++k) \
;         acc[ai][bj][m][n] = __builtin_amdgcn_mfma_f32_16x16x32_bf16(Bt[n][k], At[m][k], acc[ai][bj][m][n], 0, 0, 0); __builtin_amdgcn_s_setprio(0); } while (0)
; #define PG8_WAIT_V(n) asm volatile("s_waitcnt vmcnt(" #n ")" ::: "memory")
; #define PG8_WAIT_L(n) asm volatile("s_waitcnt lgkmcnt(" #n ")" ::: "memory")
; #define PG8_BAR __builtin_amdgcn_s_barrier()
; #define PG8_SCHED __builtin_amdgcn_sched_barrier(0)
; template <class Epi, class Sched, bool ALIGN_EPI = false, bool SP2 = false>
; __device__ __forceinline__ void gemm_phase(PG8_LAS unsigned char* lds, const Gemm g, const Sched& S, const Epi& E, int wave_s) {
;     ...
;         for (int t = 0; t < nt; t += 2) {
;     ...
;             PG8_LDB(B0, 1, 0); PG8_LDB(B1, 1, 1); PG8_SCHED; PG8_LDA(At, 1, 0); PG8_STAGE(PG8_SA(0, 1), a2 + hstep, voffA);
;             PG8_WAIT_V(8); PG8_WAIT_L(0); PG8_BAR; PG8_MMA(0, 0, At, B0); PG8_MMA(0, 1, At, B1); PG8_BAR; PG8_SCHED;
;             PG8_LDA(At, 1, 1); PG8_STAGE(PG8_SB(1, 0), b3, voffB); PG8_STAGE(PG8_SB(1, 1), b3 + hstep, voffB); PG8_STAGE(PG8_SA(1, 0), a3, voffA);
;             PG8_WAIT_V(8); PG8_WAIT_L(0); PG8_BAR; PG8_MMA(1, 0, At, B0); PG8_MMA(1, 1, At, B1); PG8_BAR; PG8_SCHED;
	s_add_i32 s45, 0, 0x18000
	s_add_i32 s86, 0, 0x1c000
	s_add_u32 s54, s54, 0x400000
	s_addc_u32 s55, s55, 0
	s_mov_b32 m0, s62
	s_nop 0
	global_load_lds_dwordx4 v184, s[54:55]
	s_mov_b32 m0, s63
	s_nop 0
	global_load_lds_dwordx4 v188, s[54:55]
	ds_read_b128 v[128:131], v230
	ds_read_b128 v[132:135], v230 offset:1024
	ds_read_b128 v[136:139], v230 offset:2048
	ds_read_b128 v[140:143], v230 offset:3072
	ds_read_b128 v[144:147], v231
	ds_read_b128 v[148:151], v231 offset:1024
	ds_read_b128 v[152:155], v231 offset:2048
	ds_read_b128 v[156:159], v231 offset:3072
	ds_read_b128 v[160:163], v213 offset:32768
	ds_read_b128 v[164:167], v213 offset:33792
	ds_read_b128 v[168:171], v213 offset:34816
	ds_read_b128 v[172:175], v213 offset:35840
	ds_read_b128 v[176:179], v213 offset:36864
	ds_read_b128 v[180:183], v213 offset:37888
	ds_read_b128 v[196:199], v213 offset:38912
	ds_read_b128 v[200:203], v213 offset:39936
	s_waitcnt vmcnt(8)
	s_waitcnt lgkmcnt(0)
	s_barrier
	v_mfma_f32_16x16x32_bf16 v[124:127], v[128:131], v[160:163], v[124:127]
	v_mfma_f32_16x16x32_bf16 v[124:127], v[132:135], v[164:167], v[124:127]
	v_mfma_f32_16x16x32_bf16 v[120:123], v[140:143], v[164:167], v[120:123]
	v_mfma_f32_16x16x32_bf16 v[120:123], v[136:139], v[160:163], v[120:123]
	v_mfma_f32_16x16x32_bf16 v[104:107], v[136:139], v[168:171], v[104:107]
	v_mfma_f32_16x16x32_bf16 v[104:107], v[140:143], v[172:175], v[104:107]
	v_mfma_f32_16x16x32_bf16 v[108:111], v[132:135], v[172:175], v[108:111]
	v_mfma_f32_16x16x32_bf16 v[108:111], v[128:131], v[168:171], v[108:111]
	v_mfma_f32_16x16x32_bf16 v[92:95], v[128:131], v[176:179], v[92:95]
	v_mfma_f32_16x16x32_bf16 v[92:95], v[132:135], v[180:183], v[92:95]
	v_mfma_f32_16x16x32_bf16 v[88:91], v[140:143], v[180:183], v[88:91]
	v_mfma_f32_16x16x32_bf16 v[88:91], v[136:139], v[176:179], v[88:91]
	v_mfma_f32_16x16x32_bf16 v[72:75], v[136:139], v[196:199], v[72:75]
	v_mfma_f32_16x16x32_bf16 v[72:75], v[140:143], v[200:203], v[72:75]
	v_mfma_f32_16x16x32_bf16 v[76:79], v[132:135], v[200:203], v[76:79]
	v_mfma_f32_16x16x32_bf16 v[76:79], v[128:131], v[196:199], v[76:79]
	v_mfma_f32_16x16x32_bf16 v[116:119], v[144:147], v[160:163], v[116:119]
	v_mfma_f32_16x16x32_bf16 v[116:119], v[148:151], v[164:167], v[116:119]
	v_mfma_f32_16x16x32_bf16 v[112:115], v[156:159], v[164:167], v[112:115]
	v_mfma_f32_16x16x32_bf16 v[112:115], v[152:155], v[160:163], v[112:115]
	v_mfma_f32_16x16x32_bf16 v[96:99], v[152:155], v[168:171], v[96:99]
	v_mfma_f32_16x16x32_bf16 v[96:99], v[156:159], v[172:175], v[96:99]
	v_mfma_f32_16x16x32_bf16 v[100:103], v[148:151], v[172:175], v[100:103]
	v_mfma_f32_16x16x32_bf16 v[100:103], v[144:147], v[168:171], v[100:103]
	v_mfma_f32_16x16x32_bf16 v[84:87], v[144:147], v[176:179], v[84:87]
	v_mfma_f32_16x16x32_bf16 v[84:87], v[148:151], v[180:183], v[84:87]
	v_mfma_f32_16x16x32_bf16 v[80:83], v[156:159], v[180:183], v[80:83]
	v_mfma_f32_16x16x32_bf16 v[80:83], v[152:155], v[176:179], v[80:83]
	v_mfma_f32_16x16x32_bf16 v[64:67], v[152:155], v[196:199], v[64:67]
	v_mfma_f32_16x16x32_bf16 v[64:67], v[156:159], v[200:203], v[64:67]
	v_mfma_f32_16x16x32_bf16 v[68:71], v[148:151], v[200:203], v[68:71]
	v_mfma_f32_16x16x32_bf16 v[68:71], v[144:147], v[196:199], v[68:71]
	s_barrier
	s_add_i32 s45, s45, s60
	s_mov_b32 m0, s45
	s_add_u32 s94, s52, 0x80
	s_addc_u32 s95, s53, 0
	global_load_lds_dwordx4 v186, s[94:95]
	s_add_i32 m0, s45, 0x2000
	s_add_u32 s52, s52, 0x400080
	s_addc_u32 s53, s53, 0
	s_add_i32 s45, s86, s60
	global_load_lds_dwordx4 v190, s[94:95]
	s_mov_b32 m0, s45
	s_nop 0
	global_load_lds_dwordx4 v186, s[52:53]
	s_add_i32 m0, s45, 0x2000
	s_nop 0
	global_load_lds_dwordx4 v190, s[52:53]
	s_mov_b32 m0, s70
	s_nop 0
	s_add_u32 s96, s54, 0xffc00080
	s_addc_u32 s97, s55, -1
	global_load_lds_dwordx4 v184, s[96:97]
	s_mov_b32 m0, s71
	s_nop 0
	global_load_lds_dwordx4 v188, s[96:97]
	ds_read_b128 v[160:163], v213 offset:49152
	ds_read_b128 v[164:167], v213 offset:50176
	ds_read_b128 v[168:171], v213 offset:51200
	ds_read_b128 v[172:175], v213 offset:52224
	ds_read_b128 v[176:179], v213 offset:53248
	ds_read_b128 v[180:183], v213 offset:54272
	ds_read_b128 v[196:199], v213 offset:55296
	ds_read_b128 v[200:203], v213 offset:56320
	s_waitcnt vmcnt(8)
	s_waitcnt lgkmcnt(0)
	s_barrier
	v_mfma_f32_16x16x32_bf16 v[60:63], v[128:131], v[160:163], v[60:63]
	v_mfma_f32_16x16x32_bf16 v[60:63], v[132:135], v[164:167], v[60:63]
	v_mfma_f32_16x16x32_bf16 v[56:59], v[140:143], v[164:167], v[56:59]
	v_mfma_f32_16x16x32_bf16 v[56:59], v[136:139], v[160:163], v[56:59]
	v_mfma_f32_16x16x32_bf16 v[40:43], v[136:139], v[168:171], v[40:43]
	v_mfma_f32_16x16x32_bf16 v[40:43], v[140:143], v[172:175], v[40:43]
	v_mfma_f32_16x16x32_bf16 v[44:47], v[132:135], v[172:175], v[44:47]
	v_mfma_f32_16x16x32_bf16 v[44:47], v[128:131], v[168:171], v[44:47]
	v_mfma_f32_16x16x32_bf16 v[28:31], v[128:131], v[176:179], v[28:31]
	v_mfma_f32_16x16x32_bf16 v[28:31], v[132:135], v[180:183], v[28:31]
	v_mfma_f32_16x16x32_bf16 v[24:27], v[140:143], v[180:183], v[24:27]
	v_mfma_f32_16x16x32_bf16 v[24:27], v[136:139], v[176:179], v[24:27]
	v_mfma_f32_16x16x32_bf16 v[8:11], v[136:139], v[196:199], v[8:11]
	v_mfma_f32_16x16x32_bf16 v[8:11], v[140:143], v[200:203], v[8:11]
	v_mfma_f32_16x16x32_bf16 v[12:15], v[132:135], v[200:203], v[12:15]
	v_mfma_f32_16x16x32_bf16 v[12:15], v[128:131], v[196:199], v[12:15]
	v_mfma_f32_16x16x32_bf16 v[52:55], v[144:147], v[160:163], v[52:55]
	v_mfma_f32_16x16x32_bf16 v[52:55], v[148:151], v[164:167], v[52:55]
	v_mfma_f32_16x16x32_bf16 v[48:51], v[156:159], v[164:167], v[48:51]
	v_mfma_f32_16x16x32_bf16 v[48:51], v[152:155], v[160:163], v[48:51]
	v_mfma_f32_16x16x32_bf16 v[32:35], v[152:155], v[168:171], v[32:35]
	v_mfma_f32_16x16x32_bf16 v[32:35], v[156:159], v[172:175], v[32:35]
	v_mfma_f32_16x16x32_bf16 v[36:39], v[148:151], v[172:175], v[36:39]
	v_mfma_f32_16x16x32_bf16 v[36:39], v[144:147], v[168:171], v[36:39]
	v_mfma_f32_16x16x32_bf16 v[20:23], v[144:147], v[176:179], v[20:23]
	v_mfma_f32_16x16x32_bf16 v[20:23], v[148:151], v[180:183], v[20:23]
	v_mfma_f32_16x16x32_bf16 v[16:19], v[156:159], v[180:183], v[16:19]
	v_mfma_f32_16x16x32_bf16 v[16:19], v[152:155], v[176:179], v[16:19]
	v_mfma_f32_16x16x32_bf16 v[0:3], v[152:155], v[196:199], v[0:3]
	v_mfma_f32_16x16x32_bf16 v[0:3], v[156:159], v[200:203], v[0:3]
	v_mfma_f32_16x16x32_bf16 v[4:7], v[148:151], v[200:203], v[4:7]
	v_mfma_f32_16x16x32_bf16 v[4:7], v[144:147], v[196:199], v[4:7]
	s_barrier
	s_add_i32 s45, s43, 2
	s_add_u32 s50, s50, 0x100
	s_addc_u32 s51, s51, 0
	s_add_u32 s7, s7, 0x100
	s_addc_u32 s41, s41, 0
	s_cmp_ge_i32 s43, s85
	s_mov_b32 s43, s45
	s_cbranch_scc0 .LBB0_1410
	s_and_b64 vcc, exec, s[20:21]
	s_cbranch_vccz .LBB0_1413
	s_barrier
